# phase 5 diagonal block via unmasked path + cndmask; accumulator zero-init hoisted under first tile loads
# speedup vs baseline: 1.0985x; 1.0114x over previous
.LBB0_36:
	v_bfe_i32 v1, v144, 27, 1
	s_waitcnt vmcnt(0)
	v_lshlrev_b32_e32 v14, 4, v144
	v_lshrrev_b32_e32 v1, 22, v1
	v_add_u32_e32 v1, v14, v1
	v_and_b32_e32 v1, 0xfffffc00, v1
	v_ashrrev_i32_e32 v0, 31, v144
	v_sub_u32_e32 v1, v14, v1
	v_lshrrev_b32_e32 v0, 26, v0
	v_lshrrev_b32_e32 v2, 4, v1
	v_add_u32_e32 v0, v144, v0
	v_bitop3_b32 v2, v2, v1, 32 bitop3:0x6c
	v_ashrrev_i32_e32 v1, 31, v1
	v_ashrrev_i32_e32 v0, 6, v0
	v_lshrrev_b32_e32 v1, 26, v1
	v_lshlrev_b32_e32 v3, 3, v0
	v_add_u32_e32 v1, v2, v1
	v_and_b32_e32 v3, -16, v3
	v_ashrrev_i32_e32 v1, 6, v1
	v_add_u32_e32 v12, v1, v3
	v_mul_i32_i24_e32 v1, 64, v1
	v_lshlrev_b32_e32 v0, 5, v0
	v_sub_u32_e32 v1, v2, v1
	v_mov_b32_e32 v5, 1
	v_and_b32_e32 v0, 32, v0
	v_ashrrev_i16_sdwa v1, v5, sext(v1) dst_sel:DWORD dst_unused:UNUSED_PAD src0_sel:DWORD src1_sel:BYTE_0
	s_add_i32 s0, s0, s1
	v_add_u32_sdwa v128, v0, sext(v1) dst_sel:DWORD dst_unused:UNUSED_PAD src0_sel:DWORD src1_sel:WORD_0
	v_add_u32_e32 v0, 0x2000, v14
	s_ashr_i32 s1, s0, 31
	v_ashrrev_i32_e32 v1, 31, v0
	s_lshr_b32 s1, s1, 28
	v_lshrrev_b32_e32 v1, 22, v1
	s_add_i32 s1, s0, s1
	v_add_u32_e32 v1, v0, v1
	s_and_b32 s2, s1, 0xfff0
	v_ashrrev_i32_e32 v1, 10, v1
	s_sub_i32 s0, s0, s2
	v_mul_i32_i24_e32 v2, 0x400, v1
	s_bfe_i32 s2, s0, 0x80000
	v_sub_u32_e32 v0, v0, v2
	s_bfe_u32 s2, s2, 0x2000d
	v_lshrrev_b32_e32 v2, 4, v0
	s_add_i32 s2, s0, s2
	v_bitop3_b32 v0, v2, v0, 32 bitop3:0x6c
	s_bfe_i32 s3, s2, 0x80000
	s_and_b32 s2, s2, 0xfc
	v_ashrrev_i32_e32 v3, 31, v0
	s_sext_i32_i16 s3, s3
	s_sub_i32 s0, s0, s2
	v_lshrrev_b32_e32 v3, 26, v3
	s_sext_i32_i8 s0, s0
	s_lshl_b32 s1, s1, 6
	s_ashr_i32 s22, s3, 2
	v_lshlrev_b32_e32 v2, 3, v1
	v_add_u32_e32 v3, v0, v3
	s_and_b32 s1, s1, 0xfffffc00
	s_lshl_b32 s23, s0, 8
	s_mul_i32 s0, s22, 0xb0000
	v_and_b32_e32 v2, -16, v2
	v_ashrrev_i32_e32 v4, 6, v3
	s_add_i32 s23, s23, s1
	s_ashr_i32 s1, s0, 31
	v_add_u32_e32 v13, v4, v2
	v_and_b32_e32 v2, 0xc0, v3
	s_lshl_b64 s[6:7], s[0:1], 1
	v_readlane_b32 s0, v254, 61
	s_movk_i32 s2, 0xb00
	v_lshlrev_b32_e32 v1, 5, v1
	v_sub_u32_e32 v0, v0, v2
	s_add_u32 s10, s18, s6
	v_add_u32_e32 v152, s0, v14
	v_mad_i64_i32 v[132:133], s[0:1], v12, s2, 0
	v_and_b32_e32 v1, 32, v1
	v_ashrrev_i16_sdwa v0, v5, sext(v0) dst_sel:DWORD dst_unused:UNUSED_PAD src0_sel:DWORD src1_sel:BYTE_0
	s_addc_u32 s11, s19, s7
	v_lshlrev_b64 v[16:17], 1, v[132:133]
	v_ashrrev_i32_e32 v129, 31, v128
	v_readfirstlane_b32 s0, v152
	v_add_u32_sdwa v130, v1, sext(v0) dst_sel:DWORD dst_unused:UNUSED_PAD src0_sel:DWORD src1_sel:WORD_0
	v_lshl_add_u64 v[2:3], s[10:11], 0, v[16:17]
	v_lshlrev_b64 v[0:1], 1, v[128:129]
	s_mov_b32 m0, s0
	v_mad_i64_i32 v[134:135], s[0:1], v13, s2, 0
	v_add_u32_e32 v153, 0x2000, v152
	v_lshl_add_u64 v[4:5], v[2:3], 0, v[0:1]
	v_readfirstlane_b32 s0, v153
	s_mul_i32 s8, s23, 0x1600
	global_load_lds_dwordx4 v[4:5], off
	v_lshlrev_b64 v[18:19], 1, v[134:135]
	v_ashrrev_i32_e32 v131, 31, v130
	s_mov_b32 m0, s0
	s_mul_hi_i32 s9, s23, 0x1600
	s_add_u32 s0, s66, s8
	v_lshl_add_u64 v[6:7], s[10:11], 0, v[18:19]
	v_lshlrev_b64 v[2:3], 1, v[130:131]
	s_addc_u32 s1, s67, s9
	v_add_u32_e32 v155, 0, v14
	v_lshl_add_u64 v[6:7], v[6:7], 0, v[2:3]
	v_lshl_add_u64 v[8:9], s[0:1], 0, v[16:17]
	v_readfirstlane_b32 s2, v155
	v_add_u32_e32 v156, 0x2000, v155
	global_load_lds_dwordx4 v[6:7], off
	v_lshl_add_u64 v[10:11], v[8:9], 0, v[0:1]
	s_mov_b32 m0, s2
	v_lshl_add_u64 v[8:9], s[0:1], 0, v[18:19]
	v_readfirstlane_b32 s0, v156
	global_load_lds_dwordx4 v[10:11], off
	s_mov_b32 m0, s0
	s_add_u32 s0, s10, 0xb0000
	v_readlane_b32 s2, v254, 62
	s_addc_u32 s1, s11, 0
	v_lshl_add_u64 v[8:9], v[8:9], 0, v[2:3]
	v_add_u32_e32 v157, s2, v14
	v_lshl_add_u64 v[20:21], s[0:1], 0, v[16:17]
	v_readfirstlane_b32 s2, v157
	global_load_lds_dwordx4 v[8:9], off
	v_lshl_add_u64 v[20:21], v[20:21], 0, v[0:1]
	s_mov_b32 m0, s2
	v_add_u32_e32 v159, 0x2000, v157
	global_load_lds_dwordx4 v[20:21], off
	v_lshl_add_u64 v[20:21], s[0:1], 0, v[18:19]
	v_readfirstlane_b32 s0, v159
	s_mov_b32 m0, s0
	s_or_b32 s0, s23, 0x80
	s_mul_hi_i32 s1, s0, 0xb00
	s_mulk_i32 s0, 0xb00
	s_lshl_b64 s[4:5], s[0:1], 1
	s_add_u32 s0, s66, s4
	s_addc_u32 s1, s67, s5
	v_add_u32_e32 v160, 0x4000, v155
	v_lshl_add_u64 v[20:21], v[20:21], 0, v[2:3]
	v_lshl_add_u64 v[16:17], s[0:1], 0, v[16:17]
	v_readfirstlane_b32 s2, v160
	global_load_lds_dwordx4 v[20:21], off
	v_lshl_add_u64 v[16:17], v[16:17], 0, v[0:1]
	s_mov_b32 m0, s2
	v_add_u32_e32 v164, 0x6000, v155
	global_load_lds_dwordx4 v[16:17], off
	v_lshl_add_u64 v[16:17], s[0:1], 0, v[18:19]
	v_readfirstlane_b32 s0, v164
	v_lshl_add_u64 v[16:17], v[16:17], 0, v[2:3]
	s_mov_b32 m0, s0
	v_ashrrev_i32_e32 v15, 8, v144
	global_load_lds_dwordx4 v[16:17], off
	v_mov_b32_e32 v21, 0
	v_mov_b32_e32 v22, 0
	v_mov_b32_e32 v23, 0
	v_mov_b32_e32 v24, 0
	v_mov_b32_e32 v25, 0
	v_mov_b32_e32 v26, 0
	v_mov_b32_e32 v27, 0
	v_mov_b32_e32 v28, 0
	v_mov_b32_e32 v29, 0
	v_mov_b32_e32 v30, 0
	v_mov_b32_e32 v31, 0
	v_mov_b32_e32 v32, 0
	v_mov_b32_e32 v33, 0
	v_mov_b32_e32 v34, 0
	v_mov_b32_e32 v35, 0
	v_mov_b32_e32 v36, 0
	v_mov_b32_e32 v37, 0
	v_mov_b32_e32 v38, 0
	v_mov_b32_e32 v39, 0
	v_mov_b32_e32 v40, 0
	v_mov_b32_e32 v41, 0
	v_mov_b32_e32 v42, 0
	v_mov_b32_e32 v43, 0
	v_mov_b32_e32 v44, 0
	v_mov_b32_e32 v45, 0
	v_mov_b32_e32 v46, 0
	v_mov_b32_e32 v47, 0
	v_mov_b32_e32 v48, 0
	v_mov_b32_e32 v49, 0
	v_mov_b32_e32 v50, 0
	v_mov_b32_e32 v51, 0
	v_mov_b32_e32 v52, 0
	v_mov_b32_e32 v53, 0
	v_mov_b32_e32 v54, 0
	v_mov_b32_e32 v55, 0
	v_mov_b32_e32 v56, 0
	v_mov_b32_e32 v57, 0
	v_mov_b32_e32 v58, 0
	v_mov_b32_e32 v59, 0
	v_mov_b32_e32 v60, 0
	v_mov_b32_e32 v61, 0
	v_mov_b32_e32 v62, 0
	v_mov_b32_e32 v63, 0
	v_mov_b32_e32 v64, 0
	v_mov_b32_e32 v65, 0
	v_mov_b32_e32 v66, 0
	v_mov_b32_e32 v67, 0
	v_mov_b32_e32 v68, 0
	v_mov_b32_e32 v69, 0
	v_mov_b32_e32 v70, 0
	v_mov_b32_e32 v71, 0
	v_mov_b32_e32 v72, 0
	v_mov_b32_e32 v73, 0
	v_mov_b32_e32 v74, 0
	v_mov_b32_e32 v75, 0
	v_mov_b32_e32 v76, 0
	v_mov_b32_e32 v77, 0
	v_mov_b32_e32 v78, 0
	v_mov_b32_e32 v79, 0
	v_mov_b32_e32 v80, 0
	v_mov_b32_e32 v81, 0
	v_mov_b32_e32 v82, 0
	v_mov_b32_e32 v83, 0
	v_mov_b32_e32 v84, 0
	v_mov_b32_e32 v85, 0
	v_mov_b32_e32 v86, 0
	v_mov_b32_e32 v87, 0
	v_mov_b32_e32 v88, 0
	v_mov_b32_e32 v89, 0
	v_mov_b32_e32 v90, 0
	v_mov_b32_e32 v91, 0
	v_mov_b32_e32 v92, 0
	v_mov_b32_e32 v93, 0
	v_mov_b32_e32 v94, 0
	v_mov_b32_e32 v95, 0
	v_mov_b32_e32 v96, 0
	v_mov_b32_e32 v97, 0
	v_mov_b32_e32 v98, 0
	v_mov_b32_e32 v99, 0
	v_mov_b32_e32 v100, 0
	v_mov_b32_e32 v101, 0
	v_mov_b32_e32 v102, 0
	v_mov_b32_e32 v103, 0
	v_mov_b32_e32 v104, 0
	v_mov_b32_e32 v105, 0
	v_mov_b32_e32 v106, 0
	v_mov_b32_e32 v107, 0
	v_mov_b32_e32 v108, 0
	v_mov_b32_e32 v109, 0
	v_mov_b32_e32 v110, 0
	v_mov_b32_e32 v111, 0
	v_mov_b32_e32 v112, 0
	v_mov_b32_e32 v113, 0
	v_mov_b32_e32 v114, 0
	v_mov_b32_e32 v115, 0
	v_mov_b32_e32 v116, 0
	v_mov_b32_e32 v117, 0
	v_mov_b32_e32 v118, 0
	v_mov_b32_e32 v119, 0
	v_mov_b32_e32 v120, 0
	v_mov_b32_e32 v121, 0
	v_mov_b32_e32 v122, 0
	v_mov_b32_e32 v123, 0
	v_mov_b32_e32 v124, 0
	v_mov_b32_e32 v125, 0
	v_mov_b32_e32 v126, 0
	v_mov_b32_e32 v127, 0
	v_not_b32_e32 v246, 63
	v_cmp_eq_u32_e32 vcc, 1, v15
	s_and_saveexec_b64 s[12:13], vcc
	s_cbranch_execz .LBB0_38
	s_barrier
.LBB0_38:
	s_or_b64 exec, exec, s[12:13]
	v_readlane_b32 s3, v254, 63
	s_mov_b64 s[12:13], 0x80
	v_lshl_add_u64 v[4:5], v[4:5], 0, s[12:13]
	v_add_u32_e32 v165, s3, v14
	v_add_u32_e32 v166, 0x2000, v165
	v_readfirstlane_b32 s0, v165
	s_mov_b32 m0, s0
	v_readfirstlane_b32 s0, v166
	v_add_u32_e32 v167, 0x8000, v155
	s_waitcnt vmcnt(4)
	s_barrier
	global_load_lds_dwordx4 v[4:5], off
	v_lshl_add_u64 v[4:5], v[6:7], 0, s[12:13]
	s_mov_b32 m0, s0
	v_readfirstlane_b32 s0, v167
	v_add_u32_e32 v168, 0xa000, v155
	global_load_lds_dwordx4 v[4:5], off
	v_lshl_add_u64 v[4:5], v[10:11], 0, s[12:13]
	s_mov_b32 m0, s0
	v_readfirstlane_b32 s0, v168
	global_load_lds_dwordx4 v[4:5], off
	s_mov_b32 m0, s0
	s_add_u32 s0, s10, 0xb0080
	v_readlane_b32 s10, v255, 0
	v_lshl_add_u64 v[4:5], v[8:9], 0, s[12:13]
	s_addc_u32 s1, s11, 0
	v_add_u32_e32 v169, s10, v14
	global_load_lds_dwordx4 v[4:5], off
	v_lshl_add_u64 v[4:5], v[132:133], 1, s[0:1]
	v_readfirstlane_b32 s2, v169
	v_lshl_add_u64 v[4:5], v[4:5], 0, v[0:1]
	s_mov_b32 m0, s2
	v_add_u32_e32 v171, 0x2000, v169
	global_load_lds_dwordx4 v[4:5], off
	v_lshl_add_u64 v[4:5], v[134:135], 1, s[0:1]
	v_readfirstlane_b32 s0, v171
	v_lshl_add_u64 v[4:5], v[4:5], 0, v[2:3]
	s_mov_b32 m0, s0
	v_and_b32_e32 v16, 15, v144
	global_load_lds_dwordx4 v[4:5], off
	v_bfe_u32 v146, v144, 4, 2
	v_lshlrev_b32_e32 v6, 2, v144
	v_lshlrev_b32_e32 v4, 4, v146
	v_lshlrev_b32_e32 v5, 6, v16
	v_and_b32_e32 v6, 32, v6
	v_bitop3_b32 v5, v4, v6, v5 bitop3:0x36
	v_readlane_b32 s0, v254, 61
	v_add_u32_e32 v11, s3, v5
	v_add_u32_e32 v14, s10, v5
	v_add_u32_e32 v9, s0, v5
	v_readlane_b32 s0, v254, 62
	v_lshl_or_b32 v147, v15, 6, v16
	v_add_u32_e32 v16, 0, v5
	v_add_u32_e32 v10, s0, v5
	v_lshlrev_b32_e32 v5, 6, v144
	s_movk_i32 s0, 0x3c0
	v_and_or_b32 v4, v5, s0, v4
	v_xad_u32 v17, v4, v6, 0
	v_mov_b64_e32 v[4:5], s[6:7]
	s_movk_i32 s2, 0x1600
	v_mad_i64_i32 v[6:7], s[0:1], v13, s2, v[4:5]
	v_mad_i64_i32 v[4:5], s[0:1], v12, s2, v[4:5]
	v_lshl_add_u64 v[138:139], v[4:5], 0, v[0:1]
	v_mov_b64_e32 v[4:5], s[8:9]
	v_lshl_add_u64 v[136:137], v[6:7], 0, v[2:3]
	v_mad_i64_i32 v[6:7], s[0:1], v13, s2, v[4:5]
	v_bfe_u32 v145, v144, 6, 2
	s_waitcnt vmcnt(6)
	v_lshlrev_b32_e32 v15, 13, v15
	v_lshl_add_u64 v[140:141], v[6:7], 0, v[2:3]
	v_mad_i64_i32 v[2:3], s[0:1], v12, s2, v[4:5]
	v_lshlrev_b32_e32 v8, 12, v145
	v_or_b32_e32 v18, 0x800, v15
	v_or_b32_e32 v19, 0x1000, v15
	v_or_b32_e32 v20, 0x1800, v15
	v_lshl_add_u64 v[142:143], v[2:3], 0, v[0:1]
	v_mov_b32_e32 v0, 0
	s_mov_b32 s0, -2
	v_add_u32_e32 v172, v9, v8
	v_add_u32_e32 v151, v16, v15
	v_add_u32_e32 v150, v17, v18
	v_add_u32_e32 v149, v17, v19
	v_add_u32_e32 v148, v17, v20
	v_add_u32_e32 v170, v10, v8
	v_add_u32_e32 v158, v11, v8
	v_add_u32_e32 v154, v14, v8
	v_mov_b32_e32 v1, v0
	v_mov_b32_e32 v2, v0
	v_mov_b32_e32 v3, v0
	v_mov_b32_e32 v4, v0
	v_mov_b32_e32 v5, v0
	v_mov_b32_e32 v6, v0
	v_mov_b32_e32 v7, v0
	v_mov_b32_e32 v8, v0
	v_mov_b32_e32 v9, v0
	v_mov_b32_e32 v10, v0
	v_mov_b32_e32 v11, v0
	v_mov_b32_e32 v12, v0
	v_mov_b32_e32 v13, v0
	v_mov_b32_e32 v14, v0
	v_mov_b32_e32 v15, v0
	v_mov_b32_e32 v16, v0
	v_mov_b32_e32 v17, v0
	v_mov_b32_e32 v18, v0
	v_mov_b32_e32 v19, v0
	v_mov_b32_e32 v20, v0
	s_mov_b64 s[2:3], 0x2600100
	s_mov_b64 s[6:7], 0x26b0100
	s_mov_b64 s[8:9], 0x2600180
	s_mov_b64 s[10:11], 0x26b0180
	s_barrier

.LBB0_47:
	v_mbcnt_lo_u32_b32 v0, -1, 0
	v_mbcnt_hi_u32_b32 v0, -1, v0
	s_ashr_i32 s0, s13, 31
	v_add_u32_e32 v140, s48, v0
	s_lshr_b32 s0, s0, 29
	v_ashrrev_i32_e32 v0, 31, v140
	v_lshrrev_b32_e32 v0, 26, v0
	v_add_u32_e32 v0, v140, v0
	v_ashrrev_i32_e32 v1, 6, v0
	v_bfe_i32 v0, v140, 27, 1
	v_lshlrev_b32_e32 v21, 4, v140
	v_lshrrev_b32_e32 v0, 22, v0
	v_add_u32_e32 v0, v21, v0
	v_and_b32_e32 v0, 0xfffffc00, v0
	v_sub_u32_e32 v0, v21, v0
	v_lshrrev_b32_e32 v2, 4, v0
	s_add_i32 s0, s13, s0
	v_bitop3_b32 v2, v2, v0, 32 bitop3:0x6c
	v_ashrrev_i32_e32 v0, 31, v0
	s_ashr_i32 s1, s0, 3
	s_and_b32 s0, s0, -8
	v_lshrrev_b32_e32 v0, 26, v0
	s_sub_i32 s0, s13, s0
	v_lshlrev_b32_e32 v3, 3, v1
	v_add_u32_e32 v0, v2, v0
	s_cmp_lt_i32 s0, 0
	s_movk_i32 s2, 0xb1
	v_and_b32_e32 v3, -16, v3
	s_waitcnt vmcnt(0)
	v_ashrrev_i32_e32 v4, 6, v0
	s_cselect_b32 s2, s2, 0xb0
	v_add_u32_e32 v0, v4, v3
	v_mul_i32_i24_e32 v3, 64, v4
	s_mul_i32 s0, s2, s0
	v_lshlrev_b32_e32 v1, 5, v1
	v_sub_u32_e32 v2, v2, v3
	v_mov_b32_e32 v7, 1
	s_add_i32 s0, s0, s1
	v_and_b32_e32 v1, 32, v1
	v_ashrrev_i16_sdwa v2, v7, sext(v2) dst_sel:DWORD dst_unused:UNUSED_PAD src0_sel:DWORD src1_sel:BYTE_0
	s_mul_hi_i32 s1, s0, 0x2e8ba2e9
	v_add_u32_sdwa v2, v1, sext(v2) dst_sel:DWORD dst_unused:UNUSED_PAD src0_sel:DWORD src1_sel:WORD_0
	v_add_u32_e32 v1, 0x2000, v21
	s_lshr_b32 s2, s1, 31
	s_ashr_i32 s1, s1, 4
	v_ashrrev_i32_e32 v3, 31, v1
	s_add_i32 s1, s1, s2
	v_lshrrev_b32_e32 v3, 22, v3
	s_mul_i32 s2, s1, 0x58
	v_add_u32_e32 v3, v1, v3
	s_sub_i32 s0, s0, s2
	v_ashrrev_i32_e32 v3, 10, v3
	s_bfe_i32 s2, s0, 0x80000
	v_mul_i32_i24_e32 v4, 0x400, v3
	s_bfe_u32 s2, s2, 0x2000d
	v_sub_u32_e32 v1, v1, v4
	s_add_i32 s2, s0, s2
	v_lshrrev_b32_e32 v4, 4, v1
	s_bfe_i32 s3, s2, 0x80000
	s_and_b32 s2, s2, 0xfc
	v_bitop3_b32 v1, v4, v1, 32 bitop3:0x6c
	s_sub_i32 s0, s0, s2
	v_ashrrev_i32_e32 v5, 31, v1
	s_sext_i32_i16 s3, s3
	s_sext_i32_i8 s0, s0
	v_lshrrev_b32_e32 v5, 26, v5
	s_lshl_b32 s1, s1, 10
	s_lshl_b32 s0, s0, 8
	s_ashr_i32 s16, s3, 2
	v_add_u32_e32 v5, v1, v5
	s_add_i32 s4, s0, s1
	s_lshl_b32 s0, s16, 8
	v_lshlrev_b32_e32 v4, 3, v3
	v_ashrrev_i32_e32 v6, 6, v5
	v_and_b32_e32 v5, 0xc0, v5
	s_ashr_i32 s1, s0, 31
	v_and_b32_e32 v4, -16, v4
	v_lshlrev_b32_e32 v3, 5, v3
	v_sub_u32_e32 v1, v1, v5
	s_lshl_b64 s[6:7], s[0:1], 11
	v_add_u32_e32 v4, v6, v4
	v_and_b32_e32 v3, 32, v3
	v_ashrrev_i16_sdwa v1, v7, sext(v1) dst_sel:DWORD dst_unused:UNUSED_PAD src0_sel:DWORD src1_sel:BYTE_0
	s_add_u32 s2, s14, s6
	v_add_u32_sdwa v6, v3, sext(v1) dst_sel:DWORD dst_unused:UNUSED_PAD src0_sel:DWORD src1_sel:WORD_0
	s_addc_u32 s3, s15, s7
	v_readlane_b32 s1, v254, 61
	v_ashrrev_i32_e32 v1, 31, v0
	v_ashrrev_i32_e32 v5, 31, v4
	s_ashr_i32 s5, s4, 31
	v_add_u32_e32 v144, s1, v21
	v_lshlrev_b64 v[0:1], 11, v[0:1]
	v_ashrrev_i32_e32 v3, 31, v2
	v_lshlrev_b64 v[4:5], 11, v[4:5]
	s_lshl_b64 s[8:9], s[4:5], 11
	v_lshl_add_u64 v[8:9], s[2:3], 0, v[0:1]
	v_lshlrev_b64 v[2:3], 1, v[2:3]
	v_readfirstlane_b32 s1, v144
	v_lshl_add_u64 v[10:11], s[2:3], 0, v[4:5]
	v_ashrrev_i32_e32 v7, 31, v6
	v_add_u32_e32 v149, 0x2000, v144
	s_add_u32 s2, s44, s8
	v_lshl_add_u64 v[8:9], v[8:9], 0, v[2:3]
	s_mov_b32 m0, s1
	v_lshlrev_b64 v[6:7], 1, v[6:7]
	v_readfirstlane_b32 s1, v149
	s_addc_u32 s3, s45, s9
	v_add_u32_e32 v151, 0, v21
	global_load_lds_dwordx4 v[8:9], off
	v_lshl_add_u64 v[10:11], v[10:11], 0, v[6:7]
	s_mov_b32 m0, s1
	v_lshl_add_u64 v[12:13], s[2:3], 0, v[0:1]
	v_readfirstlane_b32 s1, v151
	v_add_u32_e32 v152, 0x2000, v151
	global_load_lds_dwordx4 v[10:11], off
	v_lshl_add_u64 v[12:13], v[12:13], 0, v[2:3]
	s_mov_b32 m0, s1
	v_readfirstlane_b32 s1, v152
	s_bitset1_b32 s0, 7
	global_load_lds_dwordx4 v[12:13], off
	s_mov_b32 m0, s1
	s_ashr_i32 s1, s0, 31
	s_lshl_b64 s[0:1], s[0:1], 11
	v_lshl_add_u64 v[14:15], s[2:3], 0, v[4:5]
	s_add_u32 s0, s14, s0
	v_readlane_b32 s2, v254, 62
	s_addc_u32 s1, s15, s1
	v_lshl_add_u64 v[14:15], v[14:15], 0, v[6:7]
	v_add_u32_e32 v153, s2, v21
	v_lshl_add_u64 v[16:17], s[0:1], 0, v[0:1]
	v_readfirstlane_b32 s2, v153
	v_add_u32_e32 v154, 0x2000, v153
	global_load_lds_dwordx4 v[14:15], off
	v_lshl_add_u64 v[16:17], v[16:17], 0, v[2:3]
	s_mov_b32 m0, s2
	v_lshl_add_u64 v[18:19], s[0:1], 0, v[4:5]
	v_readfirstlane_b32 s0, v154
	global_load_lds_dwordx4 v[16:17], off
	s_mov_b32 m0, s0
	s_or_b32 s0, s4, 0x80
	s_ashr_i32 s1, s0, 31
	s_lshl_b64 s[0:1], s[0:1], 11
	s_add_u32 s0, s44, s0
	s_addc_u32 s1, s45, s1
	v_add_u32_e32 v156, 0x4000, v151
	v_lshl_add_u64 v[18:19], v[18:19], 0, v[6:7]
	v_lshl_add_u64 v[22:23], s[0:1], 0, v[0:1]
	v_readfirstlane_b32 s2, v156
	v_add_u32_e32 v157, 0x6000, v151
	global_load_lds_dwordx4 v[18:19], off
	v_lshl_add_u64 v[128:129], v[22:23], 0, v[2:3]
	s_mov_b32 m0, s2
	v_lshl_add_u64 v[22:23], s[0:1], 0, v[4:5]
	v_readfirstlane_b32 s0, v157
	global_load_lds_dwordx4 v[128:129], off
	v_lshl_add_u64 v[130:131], v[22:23], 0, v[6:7]
	s_mov_b32 m0, s0
	v_ashrrev_i32_e32 v20, 8, v140
	global_load_lds_dwordx4 v[130:131], off
	v_mov_b32_e32 v23, 0
	v_mov_b32_e32 v24, 0
	v_mov_b32_e32 v25, 0
	v_mov_b32_e32 v26, 0
	v_mov_b32_e32 v27, 0
	v_mov_b32_e32 v28, 0
	v_mov_b32_e32 v29, 0
	v_mov_b32_e32 v30, 0
	v_mov_b32_e32 v31, 0
	v_mov_b32_e32 v32, 0
	v_mov_b32_e32 v33, 0
	v_mov_b32_e32 v34, 0
	v_mov_b32_e32 v35, 0
	v_mov_b32_e32 v36, 0
	v_mov_b32_e32 v37, 0
	v_mov_b32_e32 v38, 0
	v_mov_b32_e32 v39, 0
	v_mov_b32_e32 v40, 0
	v_mov_b32_e32 v41, 0
	v_mov_b32_e32 v42, 0
	v_mov_b32_e32 v43, 0
	v_mov_b32_e32 v44, 0
	v_mov_b32_e32 v45, 0
	v_mov_b32_e32 v46, 0
	v_mov_b32_e32 v47, 0
	v_mov_b32_e32 v48, 0
	v_mov_b32_e32 v49, 0
	v_mov_b32_e32 v50, 0
	v_mov_b32_e32 v51, 0
	v_mov_b32_e32 v52, 0
	v_mov_b32_e32 v53, 0
	v_mov_b32_e32 v54, 0
	v_mov_b32_e32 v55, 0
	v_mov_b32_e32 v56, 0
	v_mov_b32_e32 v57, 0
	v_mov_b32_e32 v58, 0
	v_mov_b32_e32 v59, 0
	v_mov_b32_e32 v60, 0
	v_mov_b32_e32 v61, 0
	v_mov_b32_e32 v62, 0
	v_mov_b32_e32 v63, 0
	v_mov_b32_e32 v64, 0
	v_mov_b32_e32 v65, 0
	v_mov_b32_e32 v66, 0
	v_mov_b32_e32 v67, 0
	v_mov_b32_e32 v68, 0
	v_mov_b32_e32 v69, 0
	v_mov_b32_e32 v70, 0
	v_mov_b32_e32 v71, 0
	v_mov_b32_e32 v72, 0
	v_mov_b32_e32 v73, 0
	v_mov_b32_e32 v74, 0
	v_mov_b32_e32 v75, 0
	v_mov_b32_e32 v76, 0
	v_mov_b32_e32 v77, 0
	v_mov_b32_e32 v78, 0
	v_mov_b32_e32 v79, 0
	v_mov_b32_e32 v80, 0
	v_mov_b32_e32 v81, 0
	v_mov_b32_e32 v82, 0
	v_mov_b32_e32 v83, 0
	v_mov_b32_e32 v84, 0
	v_mov_b32_e32 v85, 0
	v_mov_b32_e32 v86, 0
	v_mov_b32_e32 v87, 0
	v_mov_b32_e32 v88, 0
	v_mov_b32_e32 v89, 0
	v_mov_b32_e32 v90, 0
	v_mov_b32_e32 v91, 0
	v_mov_b32_e32 v92, 0
	v_mov_b32_e32 v93, 0
	v_mov_b32_e32 v94, 0
	v_mov_b32_e32 v95, 0
	v_mov_b32_e32 v96, 0
	v_mov_b32_e32 v97, 0
	v_mov_b32_e32 v98, 0
	v_mov_b32_e32 v99, 0
	v_mov_b32_e32 v100, 0
	v_mov_b32_e32 v101, 0
	v_mov_b32_e32 v102, 0
	v_mov_b32_e32 v103, 0
	v_mov_b32_e32 v104, 0
	v_mov_b32_e32 v105, 0
	v_mov_b32_e32 v106, 0
	v_mov_b32_e32 v107, 0
	v_mov_b32_e32 v108, 0
	v_mov_b32_e32 v109, 0
	v_mov_b32_e32 v110, 0
	v_mov_b32_e32 v111, 0
	v_mov_b32_e32 v112, 0
	v_mov_b32_e32 v113, 0
	v_mov_b32_e32 v114, 0
	v_mov_b32_e32 v115, 0
	v_mov_b32_e32 v116, 0
	v_mov_b32_e32 v117, 0
	v_mov_b32_e32 v118, 0
	v_mov_b32_e32 v119, 0
	v_mov_b32_e32 v120, 0
	v_mov_b32_e32 v121, 0
	v_mov_b32_e32 v122, 0
	v_mov_b32_e32 v123, 0
	v_mov_b32_e32 v124, 0
	v_mov_b32_e32 v125, 0
	v_mov_b32_e32 v126, 0
	v_mov_b32_e32 v127, 0
	v_cmp_eq_u32_e32 vcc, 1, v20
	s_and_saveexec_b64 s[10:11], vcc
	s_cbranch_execz .LBB0_49
	s_barrier
.LBB0_49:
	s_or_b64 exec, exec, s[10:11]
	v_readlane_b32 s1, v254, 63
	s_mov_b64 s[10:11], 0x80
	v_lshl_add_u64 v[8:9], v[8:9], 0, s[10:11]
	v_add_u32_e32 v158, s1, v21
	v_add_u32_e32 v159, 0x2000, v158
	v_readfirstlane_b32 s0, v158
	s_mov_b32 m0, s0
	v_readfirstlane_b32 s0, v159
	v_add_u32_e32 v160, 0x8000, v151
	s_waitcnt vmcnt(4)
	s_barrier
	global_load_lds_dwordx4 v[8:9], off
	v_lshl_add_u64 v[8:9], v[10:11], 0, s[10:11]
	s_mov_b32 m0, s0
	v_readfirstlane_b32 s0, v160
	v_add_u32_e32 v164, 0xa000, v151
	v_readlane_b32 s2, v255, 0
	global_load_lds_dwordx4 v[8:9], off
	v_lshl_add_u64 v[8:9], v[12:13], 0, s[10:11]
	s_mov_b32 m0, s0
	v_readfirstlane_b32 s0, v164
	v_add_u32_e32 v165, s2, v21
	global_load_lds_dwordx4 v[8:9], off
	v_lshl_add_u64 v[8:9], v[14:15], 0, s[10:11]
	s_mov_b32 m0, s0
	v_readfirstlane_b32 s0, v165
	v_add_u32_e32 v167, 0x2000, v165
	global_load_lds_dwordx4 v[8:9], off
	v_lshl_add_u64 v[8:9], v[16:17], 0, s[10:11]
	s_mov_b32 m0, s0
	v_readfirstlane_b32 s0, v167
	global_load_lds_dwordx4 v[8:9], off
	v_lshl_add_u64 v[8:9], v[18:19], 0, s[10:11]
	s_mov_b32 m0, s0
	v_and_b32_e32 v22, 15, v140
	global_load_lds_dwordx4 v[8:9], off
	v_bfe_u32 v141, v140, 4, 2
	v_lshlrev_b32_e32 v11, 2, v140
	v_lshlrev_b32_e32 v8, 4, v141
	v_lshlrev_b32_e32 v9, 6, v22
	v_and_b32_e32 v11, 32, v11
	v_bitop3_b32 v9, v8, v11, v9 bitop3:0x36
	v_readlane_b32 s0, v254, 61
	v_add_u32_e32 v14, s1, v9
	v_add_u32_e32 v15, s2, v9
	v_add_u32_e32 v12, s0, v9
	v_readlane_b32 s0, v254, 62
	v_add_u32_e32 v17, 0, v9
	v_bfe_u32 v142, v140, 6, 2
	v_add_u32_e32 v13, s0, v9
	v_lshlrev_b32_e32 v9, 6, v140
	s_movk_i32 s0, 0x3c0
	v_and_or_b32 v8, v9, s0, v8
	v_xad_u32 v11, v8, v11, 0
	v_lshl_add_u64 v[8:9], s[8:9], 0, v[4:5]
	v_lshl_add_u64 v[8:9], v[8:9], 0, v[6:7]
	v_lshl_add_u64 v[132:133], s[44:45], 0, v[8:9]
	v_lshl_add_u64 v[8:9], s[8:9], 0, v[0:1]
	v_lshl_add_u64 v[0:1], s[6:7], 0, v[0:1]
	s_waitcnt vmcnt(6)
	v_lshlrev_b32_e32 v16, 13, v20
	v_lshl_add_u64 v[4:5], s[6:7], 0, v[4:5]
	v_lshl_add_u64 v[0:1], v[0:1], 0, v[2:3]
	v_lshlrev_b32_e32 v10, 12, v142
	v_lshl_or_b32 v143, v20, 6, v22
	v_or_b32_e32 v18, 0x800, v16
	v_or_b32_e32 v19, 0x1000, v16
	v_or_b32_e32 v20, 0x1800, v16
	v_lshl_add_u64 v[8:9], v[8:9], 0, v[2:3]
	v_lshl_add_u64 v[4:5], v[4:5], 0, v[6:7]
	v_lshl_add_u64 v[138:139], s[46:47], 0, v[0:1]
	v_mov_b32_e32 v0, 0
	v_lshl_add_u64 v[134:135], s[44:45], 0, v[8:9]
	v_lshl_add_u64 v[136:137], s[46:47], 0, v[4:5]
	s_mov_b32 s0, -2
	s_mov_b64 s[6:7], 0
	v_add_u32_e32 v168, v12, v10
	v_add_u32_e32 v148, v17, v16
	v_add_u32_e32 v147, v11, v18
	v_add_u32_e32 v146, v11, v19
	v_add_u32_e32 v145, v11, v20
	v_add_u32_e32 v166, v13, v10
	v_add_u32_e32 v155, v14, v10
	v_add_u32_e32 v150, v15, v10
	v_mov_b32_e32 v1, v0
	v_mov_b32_e32 v2, v0
	v_mov_b32_e32 v3, v0
	v_mov_b32_e32 v4, v0
	v_mov_b32_e32 v5, v0
	v_mov_b32_e32 v6, v0
	v_mov_b32_e32 v7, v0
	v_mov_b32_e32 v8, v0
	v_mov_b32_e32 v9, v0
	v_mov_b32_e32 v10, v0
	v_mov_b32_e32 v11, v0
	v_mov_b32_e32 v12, v0
	v_mov_b32_e32 v13, v0
	v_mov_b32_e32 v14, v0
	v_mov_b32_e32 v15, v0
	v_mov_b32_e32 v16, v0
	v_mov_b32_e32 v17, v0
	v_mov_b32_e32 v18, v0
	v_mov_b32_e32 v19, v0
	v_mov_b32_e32 v20, v0
	v_mov_b32_e32 v21, v0
	v_mov_b32_e32 v22, v0
	s_mov_b64 s[2:3], 0x1580100
	s_mov_b64 s[8:9], 0x15c0100
	s_mov_b64 s[10:11], 0x1580180
	s_mov_b64 s[18:19], 0x15c0180
	s_barrier

.LBB0_68:
	v_bfe_i32 v1, v144, 27, 1
	v_lshlrev_b32_e32 v24, 4, v144
	v_lshrrev_b32_e32 v1, 22, v1
	v_add_u32_e32 v1, v24, v1
	v_and_b32_e32 v1, 0xfffffc00, v1
	v_ashrrev_i32_e32 v0, 31, v144
	v_sub_u32_e32 v1, v24, v1
	v_lshrrev_b32_e32 v0, 26, v0
	v_lshrrev_b32_e32 v2, 4, v1
	v_add_u32_e32 v0, v144, v0
	v_bitop3_b32 v2, v2, v1, 32 bitop3:0x6c
	v_ashrrev_i32_e32 v1, 31, v1
	v_ashrrev_i32_e32 v0, 6, v0
	v_lshrrev_b32_e32 v1, 26, v1
	v_lshlrev_b32_e32 v3, 3, v0
	v_add_u32_e32 v1, v2, v1
	v_and_b32_e32 v3, -16, v3
	v_ashrrev_i32_e32 v1, 6, v1
	s_waitcnt vmcnt(0)
	v_add_u32_e32 v4, v1, v3
	v_mul_i32_i24_e32 v1, 64, v1
	v_lshlrev_b32_e32 v0, 5, v0
	v_sub_u32_e32 v1, v2, v1
	v_mov_b32_e32 v6, 1
	s_add_i32 s0, s0, s1
	v_and_b32_e32 v0, 32, v0
	v_ashrrev_i16_sdwa v1, v6, sext(v1) dst_sel:DWORD dst_unused:UNUSED_PAD src0_sel:DWORD src1_sel:BYTE_0
	s_ashr_i32 s1, s0, 31
	v_add_u32_sdwa v128, v0, sext(v1) dst_sel:DWORD dst_unused:UNUSED_PAD src0_sel:DWORD src1_sel:WORD_0
	v_add_u32_e32 v0, 0x2000, v24
	s_lshr_b32 s1, s1, 28
	v_ashrrev_i32_e32 v1, 31, v0
	s_add_i32 s1, s0, s1
	v_lshrrev_b32_e32 v1, 22, v1
	s_and_b32 s2, s1, 0xfff0
	v_add_u32_e32 v1, v0, v1
	s_sub_i32 s0, s0, s2
	v_ashrrev_i32_e32 v1, 10, v1
	s_bfe_i32 s2, s0, 0x80000
	v_mul_i32_i24_e32 v2, 0x400, v1
	s_bfe_u32 s2, s2, 0x2000d
	v_sub_u32_e32 v0, v0, v2
	s_add_i32 s2, s0, s2
	v_lshrrev_b32_e32 v2, 4, v0
	s_bfe_i32 s3, s2, 0x80000
	s_and_b32 s2, s2, 0xfc
	v_bitop3_b32 v0, v2, v0, 32 bitop3:0x6c
	s_sub_i32 s0, s0, s2
	v_ashrrev_i32_e32 v3, 31, v0
	s_sext_i32_i8 s0, s0
	s_lshl_b32 s1, s1, 6
	v_lshrrev_b32_e32 v3, 26, v3
	s_sext_i32_i16 s3, s3
	s_and_b32 s1, s1, 0xfffffc00
	s_lshl_b32 s0, s0, 8
	v_lshlrev_b32_e32 v2, 3, v1
	v_add_u32_e32 v3, v0, v3
	s_add_i32 s6, s0, s1
	s_lshl_b32 s0, s3, 6
	v_and_b32_e32 v2, -16, v2
	v_ashrrev_i32_e32 v5, 6, v3
	s_and_b32 s4, s0, 0xffffff00
	v_add_u32_e32 v10, v5, v2
	v_and_b32_e32 v2, 0xc0, v3
	s_ashr_i32 s5, s4, 31
	v_lshlrev_b32_e32 v1, 5, v1
	v_sub_u32_e32 v0, v0, v2
	s_lshl_b64 s[10:11], s[4:5], 11
	v_and_b32_e32 v1, 32, v1
	v_ashrrev_i16_sdwa v0, v6, sext(v0) dst_sel:DWORD dst_unused:UNUSED_PAD src0_sel:DWORD src1_sel:BYTE_0
	s_add_u32 s0, s22, s10
	v_ashrrev_i32_e32 v5, 31, v4
	v_add_u32_sdwa v130, v1, sext(v0) dst_sel:DWORD dst_unused:UNUSED_PAD src0_sel:DWORD src1_sel:WORD_0
	s_addc_u32 s1, s23, s11
	v_readlane_b32 s2, v254, 61
	v_lshlrev_b64 v[0:1], 11, v[4:5]
	v_ashrrev_i32_e32 v129, 31, v128
	v_add_u32_e32 v152, s2, v24
	v_lshl_add_u64 v[6:7], s[0:1], 0, v[0:1]
	v_lshlrev_b64 v[2:3], 1, v[128:129]
	v_ashrrev_i32_e32 v11, 31, v10
	v_lshl_add_u64 v[12:13], v[6:7], 0, v[2:3]
	v_readfirstlane_b32 s2, v152
	v_lshlrev_b64 v[6:7], 11, v[10:11]
	v_add_u32_e32 v154, 0x2000, v152
	s_ashr_i32 s7, s6, 31
	s_mov_b32 m0, s2
	v_lshl_add_u64 v[14:15], s[0:1], 0, v[6:7]
	v_readfirstlane_b32 s0, v154
	s_lshl_b64 s[12:13], s[6:7], 11
	global_load_lds_dwordx4 v[12:13], off
	v_ashrrev_i32_e32 v131, 31, v130
	s_mov_b32 m0, s0
	s_add_u32 s0, s20, s12
	v_lshlrev_b64 v[8:9], 1, v[130:131]
	s_addc_u32 s1, s21, s13
	v_add_u32_e32 v155, 0, v24
	v_lshl_add_u64 v[14:15], v[14:15], 0, v[8:9]
	v_lshl_add_u64 v[16:17], s[0:1], 0, v[0:1]
	v_readfirstlane_b32 s2, v155
	v_add_u32_e32 v156, 0x2000, v155
	global_load_lds_dwordx4 v[14:15], off
	v_lshl_add_u64 v[16:17], v[16:17], 0, v[2:3]
	s_mov_b32 m0, s2
	v_lshl_add_u64 v[18:19], s[0:1], 0, v[6:7]
	v_readfirstlane_b32 s0, v156
	global_load_lds_dwordx4 v[16:17], off
	s_mov_b32 m0, s0
	s_or_b32 s0, s4, 0x80
	s_ashr_i32 s1, s0, 31
	s_lshl_b64 s[0:1], s[0:1], 11
	s_add_u32 s0, s22, s0
	v_readlane_b32 s2, v254, 62
	s_addc_u32 s1, s23, s1
	v_lshl_add_u64 v[18:19], v[18:19], 0, v[8:9]
	v_add_u32_e32 v158, s2, v24
	v_lshl_add_u64 v[20:21], s[0:1], 0, v[0:1]
	v_readfirstlane_b32 s2, v158
	v_add_u32_e32 v159, 0x2000, v158
	s_or_b32 s8, s6, 0x80
	global_load_lds_dwordx4 v[18:19], off
	v_lshl_add_u64 v[20:21], v[20:21], 0, v[2:3]
	s_mov_b32 m0, s2
	v_lshl_add_u64 v[22:23], s[0:1], 0, v[6:7]
	v_readfirstlane_b32 s0, v159
	s_ashr_i32 s9, s8, 31
	global_load_lds_dwordx4 v[20:21], off
	s_mov_b32 m0, s0
	s_lshl_b64 s[0:1], s[8:9], 11
	s_add_u32 s0, s20, s0
	s_addc_u32 s1, s21, s1
	v_add_u32_e32 v160, 0x4000, v155
	v_lshl_add_u64 v[22:23], v[22:23], 0, v[8:9]
	v_lshl_add_u64 v[26:27], s[0:1], 0, v[0:1]
	v_readfirstlane_b32 s2, v160
	global_load_lds_dwordx4 v[22:23], off
	v_lshl_add_u64 v[26:27], v[26:27], 0, v[2:3]
	s_mov_b32 m0, s2
	v_add_u32_e32 v164, 0x6000, v155
	global_load_lds_dwordx4 v[26:27], off
	v_lshl_add_u64 v[26:27], s[0:1], 0, v[6:7]
	v_readfirstlane_b32 s0, v164
	v_lshl_add_u64 v[26:27], v[26:27], 0, v[8:9]
	s_mov_b32 m0, s0
	v_ashrrev_i32_e32 v25, 8, v144
	global_load_lds_dwordx4 v[26:27], off
	v_mov_b32_e32 v26, 0
	v_mov_b32_e32 v27, 0
	v_mov_b32_e32 v28, 0
	v_mov_b32_e32 v29, 0
	v_mov_b32_e32 v30, 0
	v_mov_b32_e32 v31, 0
	v_mov_b32_e32 v32, 0
	v_mov_b32_e32 v33, 0
	v_mov_b32_e32 v34, 0
	v_mov_b32_e32 v35, 0
	v_mov_b32_e32 v36, 0
	v_mov_b32_e32 v37, 0
	v_mov_b32_e32 v38, 0
	v_mov_b32_e32 v39, 0
	v_mov_b32_e32 v40, 0
	v_mov_b32_e32 v41, 0
	v_mov_b32_e32 v42, 0
	v_mov_b32_e32 v43, 0
	v_mov_b32_e32 v44, 0
	v_mov_b32_e32 v45, 0
	v_mov_b32_e32 v46, 0
	v_mov_b32_e32 v47, 0
	v_mov_b32_e32 v48, 0
	v_mov_b32_e32 v49, 0
	v_mov_b32_e32 v50, 0
	v_mov_b32_e32 v51, 0
	v_mov_b32_e32 v52, 0
	v_mov_b32_e32 v53, 0
	v_mov_b32_e32 v54, 0
	v_mov_b32_e32 v55, 0
	v_mov_b32_e32 v56, 0
	v_mov_b32_e32 v57, 0
	v_mov_b32_e32 v58, 0
	v_mov_b32_e32 v59, 0
	v_mov_b32_e32 v60, 0
	v_mov_b32_e32 v61, 0
	v_mov_b32_e32 v62, 0
	v_mov_b32_e32 v63, 0
	v_mov_b32_e32 v64, 0
	v_mov_b32_e32 v65, 0
	v_mov_b32_e32 v66, 0
	v_mov_b32_e32 v67, 0
	v_mov_b32_e32 v68, 0
	v_mov_b32_e32 v69, 0
	v_mov_b32_e32 v70, 0
	v_mov_b32_e32 v71, 0
	v_mov_b32_e32 v72, 0
	v_mov_b32_e32 v73, 0
	v_mov_b32_e32 v74, 0
	v_mov_b32_e32 v75, 0
	v_mov_b32_e32 v76, 0
	v_mov_b32_e32 v77, 0
	v_mov_b32_e32 v78, 0
	v_mov_b32_e32 v79, 0
	v_mov_b32_e32 v80, 0
	v_mov_b32_e32 v81, 0
	v_mov_b32_e32 v82, 0
	v_mov_b32_e32 v83, 0
	v_mov_b32_e32 v84, 0
	v_mov_b32_e32 v85, 0
	v_mov_b32_e32 v86, 0
	v_mov_b32_e32 v87, 0
	v_mov_b32_e32 v88, 0
	v_mov_b32_e32 v89, 0
	v_mov_b32_e32 v90, 0
	v_mov_b32_e32 v91, 0
	v_mov_b32_e32 v92, 0
	v_mov_b32_e32 v93, 0
	v_mov_b32_e32 v94, 0
	v_mov_b32_e32 v95, 0
	v_mov_b32_e32 v96, 0
	v_mov_b32_e32 v97, 0
	v_mov_b32_e32 v98, 0
	v_mov_b32_e32 v99, 0
	v_mov_b32_e32 v100, 0
	v_mov_b32_e32 v101, 0
	v_mov_b32_e32 v102, 0
	v_mov_b32_e32 v103, 0
	v_mov_b32_e32 v104, 0
	v_mov_b32_e32 v105, 0
	v_mov_b32_e32 v106, 0
	v_mov_b32_e32 v107, 0
	v_mov_b32_e32 v108, 0
	v_mov_b32_e32 v109, 0
	v_mov_b32_e32 v110, 0
	v_mov_b32_e32 v111, 0
	v_mov_b32_e32 v112, 0
	v_mov_b32_e32 v113, 0
	v_mov_b32_e32 v114, 0
	v_mov_b32_e32 v115, 0
	v_mov_b32_e32 v116, 0
	v_mov_b32_e32 v117, 0
	v_mov_b32_e32 v118, 0
	v_mov_b32_e32 v119, 0
	v_mov_b32_e32 v120, 0
	v_mov_b32_e32 v121, 0
	v_mov_b32_e32 v122, 0
	v_mov_b32_e32 v123, 0
	v_mov_b32_e32 v124, 0
	v_mov_b32_e32 v125, 0
	v_mov_b32_e32 v126, 0
	v_mov_b32_e32 v127, 0
	v_cmp_eq_u32_e32 vcc, 1, v25
	s_and_saveexec_b64 s[14:15], vcc
	s_cbranch_execz .LBB0_70
	s_barrier
.LBB0_70:
	s_or_b64 exec, exec, s[14:15]
	v_readlane_b32 s1, v254, 63
	s_mov_b64 s[14:15], 0x80
	v_lshlrev_b64 v[134:135], 10, v[4:5]
	v_add_u32_e32 v165, s1, v24
	v_add_u32_e32 v166, 0x2000, v165
	v_readfirstlane_b32 s0, v165
	v_lshl_add_u64 v[4:5], v[12:13], 0, s[14:15]
	s_mov_b32 m0, s0
	v_readfirstlane_b32 s0, v166
	v_add_u32_e32 v167, 0x8000, v155
	s_waitcnt vmcnt(4)
	s_barrier
	global_load_lds_dwordx4 v[4:5], off
	v_lshl_add_u64 v[4:5], v[14:15], 0, s[14:15]
	s_mov_b32 m0, s0
	v_readfirstlane_b32 s0, v167
	v_add_u32_e32 v169, 0xa000, v155
	v_readlane_b32 s2, v255, 0
	global_load_lds_dwordx4 v[4:5], off
	v_lshl_add_u64 v[4:5], v[16:17], 0, s[14:15]
	s_mov_b32 m0, s0
	v_readfirstlane_b32 s0, v169
	v_add_u32_e32 v170, s2, v24
	global_load_lds_dwordx4 v[4:5], off
	v_lshl_add_u64 v[4:5], v[18:19], 0, s[14:15]
	s_mov_b32 m0, s0
	v_readfirstlane_b32 s0, v170
	v_add_u32_e32 v171, 0x2000, v170
	global_load_lds_dwordx4 v[4:5], off
	v_lshl_add_u64 v[4:5], v[20:21], 0, s[14:15]
	s_mov_b32 m0, s0
	v_readfirstlane_b32 s0, v171
	global_load_lds_dwordx4 v[4:5], off
	v_lshl_add_u64 v[4:5], v[22:23], 0, s[14:15]
	s_mov_b32 m0, s0
	v_lshlrev_b64 v[132:133], 10, v[10:11]
	global_load_lds_dwordx4 v[4:5], off
	v_and_b32_e32 v10, 15, v144
	v_bfe_u32 v146, v144, 4, 2
	v_lshlrev_b32_e32 v12, 2, v144
	v_lshlrev_b32_e32 v4, 4, v146
	v_lshlrev_b32_e32 v5, 6, v10
	v_and_b32_e32 v12, 32, v12
	v_bitop3_b32 v5, v4, v12, v5 bitop3:0x36
	v_readlane_b32 s0, v254, 61
	v_add_u32_e32 v15, s1, v5
	v_add_u32_e32 v16, s2, v5
	v_add_u32_e32 v13, s0, v5
	v_readlane_b32 s0, v254, 62
	v_add_u32_e32 v17, 0, v5
	v_bfe_u32 v145, v144, 6, 2
	v_add_u32_e32 v14, s0, v5
	v_lshlrev_b32_e32 v5, 6, v144
	s_movk_i32 s0, 0x3c0
	v_and_or_b32 v4, v5, s0, v4
	v_xad_u32 v12, v4, v12, 0
	v_lshl_add_u64 v[4:5], s[10:11], 0, v[6:7]
	s_waitcnt vmcnt(6)
	v_lshl_or_b32 v147, v25, 6, v10
	v_lshlrev_b32_e32 v10, 13, v25
	v_lshl_add_u64 v[136:137], v[4:5], 0, v[8:9]
	v_lshl_add_u64 v[4:5], s[10:11], 0, v[0:1]
	v_lshl_add_u64 v[0:1], s[12:13], 0, v[0:1]
	v_lshlrev_b32_e32 v11, 12, v145
	v_or_b32_e32 v18, 0x800, v10
	v_or_b32_e32 v19, 0x1000, v10
	v_or_b32_e32 v20, 0x1800, v10
	v_lshl_add_u64 v[138:139], v[4:5], 0, v[2:3]
	v_lshl_add_u64 v[4:5], s[12:13], 0, v[6:7]
	v_lshl_add_u64 v[142:143], v[0:1], 0, v[2:3]
	v_mov_b32_e32 v0, 0
	v_not_b32_e32 v246, 63
	s_lshl_b64 s[8:9], s[8:9], 10
	v_lshl_add_u64 v[140:141], v[4:5], 0, v[8:9]
	s_mov_b32 s0, -2
	v_add_u32_e32 v172, v13, v11
	v_add_u32_e32 v151, v17, v10
	v_add_u32_e32 v150, v12, v18
	v_add_u32_e32 v149, v12, v19
	v_add_u32_e32 v148, v12, v20
	v_add_u32_e32 v168, v14, v11
	v_add_u32_e32 v157, v15, v11
	v_add_u32_e32 v153, v16, v11
	v_mov_b32_e32 v1, v0
	v_mov_b32_e32 v2, v0
	v_mov_b32_e32 v3, v0
	v_mov_b32_e32 v4, v0
	v_mov_b32_e32 v5, v0
	v_mov_b32_e32 v6, v0
	v_mov_b32_e32 v7, v0
	v_mov_b32_e32 v8, v0
	v_mov_b32_e32 v9, v0
	v_mov_b32_e32 v10, v0
	v_mov_b32_e32 v11, v0
	v_mov_b32_e32 v12, v0
	v_mov_b32_e32 v13, v0
	v_mov_b32_e32 v14, v0
	v_mov_b32_e32 v15, v0
	v_mov_b32_e32 v16, v0
	v_mov_b32_e32 v17, v0
	v_mov_b32_e32 v18, v0
	v_mov_b32_e32 v19, v0
	v_mov_b32_e32 v20, v0
	v_mov_b32_e32 v21, v0
	v_mov_b32_e32 v22, v0
	v_mov_b32_e32 v23, v0
	v_mov_b32_e32 v24, v0
	v_mov_b32_e32 v25, v0
	s_mov_b64 s[2:3], 0xa778680
	s_mov_b64 s[10:11], 0x2e80100
	s_mov_b64 s[12:13], 0xa738700
	s_mov_b64 s[14:15], 0x2ec0100
	s_mov_b64 s[26:27], 0xa778700
	s_mov_b64 s[28:29], 0x2e80180
	s_mov_b64 s[30:31], 0xa738780
	s_mov_b64 s[34:35], 0x2ec0180
	s_barrier

.LBB0_113:
	v_ashrrev_i32_e32 v0, 31, v140
	v_lshrrev_b32_e32 v0, 26, v0
	v_add_u32_e32 v0, v140, v0
	v_ashrrev_i32_e32 v1, 6, v0
	v_bfe_i32 v0, v140, 27, 1
	v_lshlrev_b32_e32 v21, 4, v140
	v_lshrrev_b32_e32 v0, 22, v0
	v_add_u32_e32 v0, v21, v0
	v_and_b32_e32 v0, 0xfffffc00, v0
	v_sub_u32_e32 v0, v21, v0
	v_lshrrev_b32_e32 v2, 4, v0
	v_bitop3_b32 v2, v2, v0, 32 bitop3:0x6c
	v_ashrrev_i32_e32 v0, 31, v0
	v_lshrrev_b32_e32 v0, 26, v0
	v_lshlrev_b32_e32 v3, 3, v1
	v_add_u32_e32 v0, v2, v0
	v_and_b32_e32 v3, -16, v3
	s_waitcnt vmcnt(0)
	v_ashrrev_i32_e32 v4, 6, v0
	v_add_u32_e32 v0, v4, v3
	v_mul_i32_i24_e32 v3, 64, v4
	v_lshlrev_b32_e32 v1, 5, v1
	v_sub_u32_e32 v2, v2, v3
	v_mov_b32_e32 v7, 1
	v_and_b32_e32 v1, 32, v1
	v_ashrrev_i16_sdwa v2, v7, sext(v2) dst_sel:DWORD dst_unused:UNUSED_PAD src0_sel:DWORD src1_sel:BYTE_0
	v_add_u32_sdwa v2, v1, sext(v2) dst_sel:DWORD dst_unused:UNUSED_PAD src0_sel:DWORD src1_sel:WORD_0
	v_add_u32_e32 v1, 0x2000, v21
	v_ashrrev_i32_e32 v3, 31, v1
	v_lshrrev_b32_e32 v3, 22, v3
	v_add_u32_e32 v3, v1, v3
	v_ashrrev_i32_e32 v3, 10, v3
	v_mul_i32_i24_e32 v4, 0x400, v3
	v_sub_u32_e32 v1, v1, v4
	v_lshrrev_b32_e32 v4, 4, v1
	v_bitop3_b32 v1, v4, v1, 32 bitop3:0x6c
	s_add_i32 s1, s0, s1
	v_ashrrev_i32_e32 v5, 31, v1
	s_mul_hi_i32 s0, s1, 0x2aaaaaab
	v_lshrrev_b32_e32 v5, 26, v5
	s_lshr_b32 s2, s0, 31
	s_ashr_i32 s0, s0, 2
	v_add_u32_e32 v5, v1, v5
	s_add_i32 s2, s0, s2
	v_ashrrev_i32_e32 v6, 6, v5
	v_and_b32_e32 v5, 0xc0, v5
	s_lshl_b32 s12, s2, 2
	v_lshlrev_b32_e32 v4, 3, v3
	v_lshlrev_b32_e32 v3, 5, v3
	v_sub_u32_e32 v1, v1, v5
	s_sub_i32 s0, 0x42, s12
	v_and_b32_e32 v4, -16, v4
	v_and_b32_e32 v3, 32, v3
	v_ashrrev_i16_sdwa v1, v7, sext(v1) dst_sel:DWORD dst_unused:UNUSED_PAD src0_sel:DWORD src1_sel:BYTE_0
	s_min_u32 s13, s0, 4
	s_mul_i32 s3, s2, 24
	v_add_u32_e32 v4, v6, v4
	v_add_u32_sdwa v6, v3, sext(v1) dst_sel:DWORD dst_unused:UNUSED_PAD src0_sel:DWORD src1_sel:WORD_0
	s_sub_i32 s14, s1, s3
	v_cvt_f32_ubyte0_e32 v3, s13
	v_cvt_f32_i32_e32 v1, s14
	v_rcp_iflag_f32_e32 v5, v3
	s_ashr_i32 s0, s14, 30
	s_or_b32 s0, s0, 1
	v_ashrrev_i32_e32 v7, 31, v6
	v_mul_f32_e32 v5, v1, v5
	v_trunc_f32_e32 v5, v5
	v_fma_f32 v1, -v5, v3, v1
	v_cvt_i32_f32_e32 v5, v5
	v_cmp_ge_f32_e64 s[4:5], |v1|, v3
	s_and_b64 s[4:5], s[4:5], exec
	s_cselect_b32 s0, s0, 0
	v_readfirstlane_b32 s4, v5
	s_add_i32 s0, s4, s0
	s_mul_i32 s18, s0, s13
	s_sub_i32 s4, s14, s18
	s_sext_i32_i8 s4, s4
	s_sext_i32_i8 s5, s0
	s_add_i32 s12, s12, s4
	s_lshl_b32 s4, s12, 8
	s_lshl_b32 s12, s5, 8
	s_ashr_i32 s13, s12, 31
	s_lshl_b64 s[14:15], s[12:13], 11
	s_add_u32 s16, s22, s14
	v_readlane_b32 s5, v254, 61
	v_ashrrev_i32_e32 v1, 31, v0
	s_addc_u32 s17, s23, s15
	v_add_u32_e32 v143, s5, v21
	v_lshlrev_b64 v[0:1], 11, v[0:1]
	v_ashrrev_i32_e32 v3, 31, v2
	v_lshl_add_u64 v[8:9], s[16:17], 0, v[0:1]
	v_lshlrev_b64 v[2:3], 1, v[2:3]
	v_readfirstlane_b32 s5, v143
	v_add_u32_e32 v148, 0x2000, v143
	v_lshl_add_u64 v[8:9], v[8:9], 0, v[2:3]
	s_mov_b32 m0, s5
	v_ashrrev_i32_e32 v5, 31, v4
	v_readfirstlane_b32 s5, v148
	global_load_lds_dwordx4 v[8:9], off
	v_lshlrev_b64 v[4:5], 11, v[4:5]
	s_mov_b32 m0, s5
	s_ashr_i32 s5, s4, 31
	v_lshl_add_u64 v[10:11], s[16:17], 0, v[4:5]
	s_lshl_b64 s[16:17], s[4:5], 11
	s_add_u32 s16, s44, s16
	s_addc_u32 s17, s45, s17
	v_lshl_add_u64 v[12:13], s[16:17], 0, v[0:1]
	v_lshl_add_u64 v[14:15], s[16:17], 0, v[4:5]
	s_or_b32 s16, s12, 0x80
	s_ashr_i32 s17, s16, 31
	s_lshl_b64 s[16:17], s[16:17], 11
	v_lshlrev_b64 v[6:7], 1, v[6:7]
	v_add_u32_e32 v149, 0, v21
	s_add_u32 s16, s22, s16
	v_lshl_add_u64 v[10:11], v[10:11], 0, v[6:7]
	v_readfirstlane_b32 s5, v149
	v_add_u32_e32 v151, 0x2000, v149
	s_addc_u32 s17, s23, s17
	global_load_lds_dwordx4 v[10:11], off
	v_lshl_add_u64 v[12:13], v[12:13], 0, v[2:3]
	s_mov_b32 m0, s5
	v_readfirstlane_b32 s5, v151
	v_lshl_add_u64 v[16:17], s[16:17], 0, v[0:1]
	v_lshl_add_u64 v[18:19], s[16:17], 0, v[4:5]
	s_or_b32 s16, s4, 0x80
	global_load_lds_dwordx4 v[12:13], off
	s_mov_b32 m0, s5
	v_readlane_b32 s5, v254, 62
	s_ashr_i32 s17, s16, 31
	s_lshl_b64 s[16:17], s[16:17], 11
	v_add_u32_e32 v152, s5, v21
	v_lshl_add_u64 v[14:15], v[14:15], 0, v[6:7]
	v_readfirstlane_b32 s5, v152
	v_add_u32_e32 v153, 0x2000, v152
	s_add_u32 s16, s44, s16
	global_load_lds_dwordx4 v[14:15], off
	v_lshl_add_u64 v[16:17], v[16:17], 0, v[2:3]
	s_mov_b32 m0, s5
	v_readfirstlane_b32 s5, v153
	s_addc_u32 s17, s45, s17
	v_add_u32_e32 v155, 0x4000, v149
	global_load_lds_dwordx4 v[16:17], off
	v_lshl_add_u64 v[18:19], v[18:19], 0, v[6:7]
	s_mov_b32 m0, s5
	v_lshl_add_u64 v[22:23], s[16:17], 0, v[0:1]
	v_readfirstlane_b32 s5, v155
	v_add_u32_e32 v156, 0x6000, v149
	global_load_lds_dwordx4 v[18:19], off
	v_lshl_add_u64 v[128:129], v[22:23], 0, v[2:3]
	s_mov_b32 m0, s5
	v_lshl_add_u64 v[22:23], s[16:17], 0, v[4:5]
	v_readfirstlane_b32 s5, v156
	global_load_lds_dwordx4 v[128:129], off
	v_lshl_add_u64 v[130:131], v[22:23], 0, v[6:7]
	s_mov_b32 m0, s5
	v_ashrrev_i32_e32 v20, 8, v140
	global_load_lds_dwordx4 v[130:131], off
	v_mov_b32_e32 v23, 0
	v_mov_b32_e32 v24, 0
	v_mov_b32_e32 v25, 0
	v_mov_b32_e32 v26, 0
	v_mov_b32_e32 v27, 0
	v_mov_b32_e32 v28, 0
	v_mov_b32_e32 v29, 0
	v_mov_b32_e32 v30, 0
	v_mov_b32_e32 v31, 0
	v_mov_b32_e32 v32, 0
	v_mov_b32_e32 v33, 0
	v_mov_b32_e32 v34, 0
	v_mov_b32_e32 v35, 0
	v_mov_b32_e32 v36, 0
	v_mov_b32_e32 v37, 0
	v_mov_b32_e32 v38, 0
	v_mov_b32_e32 v39, 0
	v_mov_b32_e32 v40, 0
	v_mov_b32_e32 v41, 0
	v_mov_b32_e32 v42, 0
	v_mov_b32_e32 v43, 0
	v_mov_b32_e32 v44, 0
	v_mov_b32_e32 v45, 0
	v_mov_b32_e32 v46, 0
	v_mov_b32_e32 v47, 0
	v_mov_b32_e32 v48, 0
	v_mov_b32_e32 v49, 0
	v_mov_b32_e32 v50, 0
	v_mov_b32_e32 v51, 0
	v_mov_b32_e32 v52, 0
	v_mov_b32_e32 v53, 0
	v_mov_b32_e32 v54, 0
	v_mov_b32_e32 v55, 0
	v_mov_b32_e32 v56, 0
	v_mov_b32_e32 v57, 0
	v_mov_b32_e32 v58, 0
	v_mov_b32_e32 v59, 0
	v_mov_b32_e32 v60, 0
	v_mov_b32_e32 v61, 0
	v_mov_b32_e32 v62, 0
	v_mov_b32_e32 v63, 0
	v_mov_b32_e32 v64, 0
	v_mov_b32_e32 v65, 0
	v_mov_b32_e32 v66, 0
	v_mov_b32_e32 v67, 0
	v_mov_b32_e32 v68, 0
	v_mov_b32_e32 v69, 0
	v_mov_b32_e32 v70, 0
	v_mov_b32_e32 v71, 0
	v_mov_b32_e32 v72, 0
	v_mov_b32_e32 v73, 0
	v_mov_b32_e32 v74, 0
	v_mov_b32_e32 v75, 0
	v_mov_b32_e32 v76, 0
	v_mov_b32_e32 v77, 0
	v_mov_b32_e32 v78, 0
	v_mov_b32_e32 v79, 0
	v_mov_b32_e32 v80, 0
	v_mov_b32_e32 v81, 0
	v_mov_b32_e32 v82, 0
	v_mov_b32_e32 v83, 0
	v_mov_b32_e32 v84, 0
	v_mov_b32_e32 v85, 0
	v_mov_b32_e32 v86, 0
	v_mov_b32_e32 v87, 0
	v_mov_b32_e32 v88, 0
	v_mov_b32_e32 v89, 0
	v_mov_b32_e32 v90, 0
	v_mov_b32_e32 v91, 0
	v_mov_b32_e32 v92, 0
	v_mov_b32_e32 v93, 0
	v_mov_b32_e32 v94, 0
	v_mov_b32_e32 v95, 0
	v_mov_b32_e32 v96, 0
	v_mov_b32_e32 v97, 0
	v_mov_b32_e32 v98, 0
	v_mov_b32_e32 v99, 0
	v_mov_b32_e32 v100, 0
	v_mov_b32_e32 v101, 0
	v_mov_b32_e32 v102, 0
	v_mov_b32_e32 v103, 0
	v_mov_b32_e32 v104, 0
	v_mov_b32_e32 v105, 0
	v_mov_b32_e32 v106, 0
	v_mov_b32_e32 v107, 0
	v_mov_b32_e32 v108, 0
	v_mov_b32_e32 v109, 0
	v_mov_b32_e32 v110, 0
	v_mov_b32_e32 v111, 0
	v_mov_b32_e32 v112, 0
	v_mov_b32_e32 v113, 0
	v_mov_b32_e32 v114, 0
	v_mov_b32_e32 v115, 0
	v_mov_b32_e32 v116, 0
	v_mov_b32_e32 v117, 0
	v_mov_b32_e32 v118, 0
	v_mov_b32_e32 v119, 0
	v_mov_b32_e32 v120, 0
	v_mov_b32_e32 v121, 0
	v_mov_b32_e32 v122, 0
	v_mov_b32_e32 v123, 0
	v_mov_b32_e32 v124, 0
	v_mov_b32_e32 v125, 0
	v_mov_b32_e32 v126, 0
	v_mov_b32_e32 v127, 0
	v_cmp_eq_u32_e32 vcc, 1, v20
	s_and_saveexec_b64 s[16:17], vcc
	s_cbranch_execz .LBB0_115
	s_barrier
.LBB0_115:
	s_or_b64 exec, exec, s[16:17]
	v_readlane_b32 s16, v254, 63
	s_mov_b64 s[24:25], 0x80
	v_lshl_add_u64 v[8:9], v[8:9], 0, s[24:25]
	v_add_u32_e32 v157, s16, v21
	v_add_u32_e32 v158, 0x2000, v157
	v_readfirstlane_b32 s5, v157
	s_mov_b32 m0, s5
	v_readfirstlane_b32 s5, v158
	v_add_u32_e32 v159, 0x8000, v149
	s_waitcnt vmcnt(4)
	s_barrier
	global_load_lds_dwordx4 v[8:9], off
	v_lshl_add_u64 v[8:9], v[10:11], 0, s[24:25]
	s_mov_b32 m0, s5
	v_readfirstlane_b32 s5, v159
	v_add_u32_e32 v160, 0xa000, v149
	v_readlane_b32 s17, v255, 0
	global_load_lds_dwordx4 v[8:9], off
	v_lshl_add_u64 v[8:9], v[12:13], 0, s[24:25]
	s_mov_b32 m0, s5
	v_readfirstlane_b32 s5, v160
	v_add_u32_e32 v164, s17, v21
	global_load_lds_dwordx4 v[8:9], off
	v_lshl_add_u64 v[8:9], v[14:15], 0, s[24:25]
	s_mov_b32 m0, s5
	v_readfirstlane_b32 s5, v164
	v_add_u32_e32 v165, 0x2000, v164
	global_load_lds_dwordx4 v[8:9], off
	v_lshl_add_u64 v[8:9], v[16:17], 0, s[24:25]
	s_mov_b32 m0, s5
	v_readfirstlane_b32 s5, v165
	global_load_lds_dwordx4 v[8:9], off
	v_lshl_add_u64 v[8:9], v[18:19], 0, s[24:25]
	s_mov_b32 m0, s5
	s_sub_i32 s1, s1, s18
	global_load_lds_dwordx4 v[8:9], off
	v_and_b32_e32 v22, 15, v140
	v_lshlrev_b32_e32 v141, 2, v140
	s_sub_i32 s1, s1, s3
	v_and_b32_e32 v8, 48, v140
	v_lshlrev_b32_e32 v9, 6, v22
	v_and_b32_e32 v11, 32, v141
	s_sext_i32_i8 s1, s1
	v_bitop3_b32 v9, v9, v11, v8 bitop3:0x36
	v_readlane_b32 s5, v254, 61
	s_lshl_b32 s2, s2, 10
	s_lshl_b32 s1, s1, 8
	v_add_u32_e32 v12, s5, v9
	v_readlane_b32 s5, v254, 62
	s_add_i32 s2, s2, s1
	v_add_u32_e32 v14, s16, v9
	v_add_u32_e32 v13, s5, v9
	v_add_u32_e32 v15, s17, v9
	v_add_u32_e32 v17, 0, v9
	v_lshlrev_b32_e32 v9, 6, v140
	s_movk_i32 s5, 0x3c0
	s_ashr_i32 s3, s2, 31
	v_and_or_b32 v8, v9, s5, v8
	s_lshl_b64 s[2:3], s[2:3], 11
	v_xad_u32 v11, v8, v11, 0
	v_lshl_add_u64 v[8:9], s[2:3], 0, v[4:5]
	v_lshl_add_u64 v[8:9], v[8:9], 0, v[6:7]
	v_lshl_add_u64 v[132:133], s[44:45], 0, v[8:9]
	v_lshl_add_u64 v[8:9], s[2:3], 0, v[0:1]
	v_lshl_add_u64 v[0:1], s[14:15], 0, v[0:1]
	v_bfe_u32 v169, v140, 6, 2
	s_waitcnt vmcnt(6)
	v_lshlrev_b32_e32 v16, 13, v20
	v_lshl_add_u64 v[4:5], s[14:15], 0, v[4:5]
	v_lshl_add_u64 v[0:1], v[0:1], 0, v[2:3]
	v_lshlrev_b32_e32 v10, 12, v169
	v_lshl_or_b32 v142, v20, 6, v22
	v_or_b32_e32 v18, 0x800, v16
	v_or_b32_e32 v19, 0x1000, v16
	v_or_b32_e32 v20, 0x1800, v16
	v_lshl_add_u64 v[8:9], v[8:9], 0, v[2:3]
	v_lshl_add_u64 v[4:5], v[4:5], 0, v[6:7]
	v_lshl_add_u64 v[138:139], s[46:47], 0, v[0:1]
	v_mov_b32_e32 v0, 0
	s_lshl_b32 s0, s0, 24
	v_lshl_add_u64 v[134:135], s[44:45], 0, v[8:9]
	v_lshl_add_u64 v[136:137], s[46:47], 0, v[4:5]
	s_mov_b32 s1, -2
	s_mov_b64 s[14:15], 0
	v_add_u32_e32 v167, v12, v10
	v_add_u32_e32 v147, v17, v16
	v_add_u32_e32 v146, v11, v18
	v_add_u32_e32 v145, v11, v19
	v_add_u32_e32 v144, v11, v20
	v_add_u32_e32 v166, v13, v10
	v_add_u32_e32 v154, v14, v10
	v_add_u32_e32 v150, v15, v10
	v_mov_b32_e32 v1, v0
	v_mov_b32_e32 v2, v0
	v_mov_b32_e32 v3, v0
	v_mov_b32_e32 v4, v0
	v_mov_b32_e32 v5, v0
	v_mov_b32_e32 v6, v0
	v_mov_b32_e32 v7, v0
	v_mov_b32_e32 v8, v0
	v_mov_b32_e32 v9, v0
	v_mov_b32_e32 v10, v0
	v_mov_b32_e32 v11, v0
	v_mov_b32_e32 v12, v0
	v_mov_b32_e32 v13, v0
	v_mov_b32_e32 v14, v0
	v_mov_b32_e32 v15, v0
	v_mov_b32_e32 v16, v0
	v_mov_b32_e32 v17, v0
	v_mov_b32_e32 v18, v0
	v_mov_b32_e32 v19, v0
	v_mov_b32_e32 v20, v0
	v_mov_b32_e32 v21, v0
	v_mov_b32_e32 v22, v0
	s_waitcnt vmcnt(0)
	s_mov_b64 s[16:17], 0x2b80100
	s_mov_b64 s[18:19], 0x2bc0100
	s_mov_b64 s[24:25], 0x2b80180
	s_mov_b64 s[26:27], 0x2bc0180
	s_barrier

.LBB0_186:
	v_bfe_i32 v1, v144, 27, 1
	s_waitcnt vmcnt(0)
	v_lshlrev_b32_e32 v14, 4, v144
	v_lshrrev_b32_e32 v1, 22, v1
	v_add_u32_e32 v1, v14, v1
	v_and_b32_e32 v1, 0xfffffc00, v1
	v_ashrrev_i32_e32 v0, 31, v144
	v_sub_u32_e32 v1, v14, v1
	v_lshrrev_b32_e32 v0, 26, v0
	v_lshrrev_b32_e32 v2, 4, v1
	v_add_u32_e32 v0, v144, v0
	v_bitop3_b32 v2, v2, v1, 32 bitop3:0x6c
	v_ashrrev_i32_e32 v1, 31, v1
	v_ashrrev_i32_e32 v0, 6, v0
	v_lshrrev_b32_e32 v1, 26, v1
	v_lshlrev_b32_e32 v3, 3, v0
	v_add_u32_e32 v1, v2, v1
	v_and_b32_e32 v3, -16, v3
	v_ashrrev_i32_e32 v1, 6, v1
	v_add_u32_e32 v12, v1, v3
	v_mul_i32_i24_e32 v1, 64, v1
	v_lshlrev_b32_e32 v0, 5, v0
	v_sub_u32_e32 v1, v2, v1
	v_mov_b32_e32 v5, 1
	v_and_b32_e32 v0, 32, v0
	v_ashrrev_i16_sdwa v1, v5, sext(v1) dst_sel:DWORD dst_unused:UNUSED_PAD src0_sel:DWORD src1_sel:BYTE_0
	v_add_u32_sdwa v128, v0, sext(v1) dst_sel:DWORD dst_unused:UNUSED_PAD src0_sel:DWORD src1_sel:WORD_0
	v_add_u32_e32 v0, 0x2000, v14
	v_ashrrev_i32_e32 v1, 31, v0
	v_lshrrev_b32_e32 v1, 22, v1
	v_add_u32_e32 v1, v0, v1
	v_ashrrev_i32_e32 v1, 10, v1
	v_mul_i32_i24_e32 v2, 0x400, v1
	v_sub_u32_e32 v0, v0, v2
	v_lshrrev_b32_e32 v2, 4, v0
	v_bitop3_b32 v0, v2, v0, 32 bitop3:0x6c
	v_ashrrev_i32_e32 v3, 31, v0
	s_mul_i32 s2, s21, 0xb0000
	v_lshrrev_b32_e32 v3, 26, v3
	s_ashr_i32 s3, s2, 31
	v_lshlrev_b32_e32 v2, 3, v1
	v_add_u32_e32 v3, v0, v3
	s_lshl_b64 s[4:5], s[2:3], 1
	v_and_b32_e32 v2, -16, v2
	v_ashrrev_i32_e32 v4, 6, v3
	s_add_u32 s2, s16, s4
	v_add_u32_e32 v13, v4, v2
	v_and_b32_e32 v2, 0xc0, v3
	s_addc_u32 s3, s17, s5
	s_lshl_b32 s68, s8, 1
	s_movk_i32 s22, 0xb00
	v_lshlrev_b32_e32 v1, 5, v1
	v_sub_u32_e32 v0, v0, v2
	s_add_u32 s10, s2, s68
	v_readlane_b32 s1, v254, 61
	v_mad_i64_i32 v[132:133], s[8:9], v12, s22, 0
	v_and_b32_e32 v1, 32, v1
	v_ashrrev_i16_sdwa v0, v5, sext(v0) dst_sel:DWORD dst_unused:UNUSED_PAD src0_sel:DWORD src1_sel:BYTE_0
	s_addc_u32 s11, s3, 0
	v_add_u32_e32 v148, s1, v14
	v_lshlrev_b64 v[16:17], 1, v[132:133]
	v_ashrrev_i32_e32 v129, 31, v128
	v_add_u32_sdwa v130, v1, sext(v0) dst_sel:DWORD dst_unused:UNUSED_PAD src0_sel:DWORD src1_sel:WORD_0
	v_lshl_add_u64 v[2:3], s[10:11], 0, v[16:17]
	v_lshlrev_b64 v[0:1], 1, v[128:129]
	v_readfirstlane_b32 s1, v148
	v_mad_i64_i32 v[134:135], s[8:9], v13, s22, 0
	v_add_u32_e32 v153, 0x2000, v148
	v_lshl_add_u64 v[4:5], v[2:3], 0, v[0:1]
	s_mov_b32 m0, s1
	v_readfirstlane_b32 s1, v153
	s_mul_i32 s8, s20, 0x1600
	global_load_lds_dwordx4 v[4:5], off
	s_mov_b32 m0, s1
	s_mul_hi_i32 s9, s20, 0x1600
	s_add_u32 s1, s66, s8
	s_addc_u32 s23, s67, s9
	v_lshlrev_b64 v[18:19], 1, v[134:135]
	v_ashrrev_i32_e32 v131, 31, v130
	s_add_u32 s22, s1, s68
	v_lshl_add_u64 v[6:7], s[10:11], 0, v[18:19]
	v_lshlrev_b64 v[2:3], 1, v[130:131]
	s_addc_u32 s23, s23, 0
	v_add_u32_e32 v155, 0, v14
	v_lshl_add_u64 v[6:7], v[6:7], 0, v[2:3]
	v_lshl_add_u64 v[8:9], s[22:23], 0, v[16:17]
	v_readfirstlane_b32 s1, v155
	v_add_u32_e32 v156, 0x2000, v155
	global_load_lds_dwordx4 v[6:7], off
	v_lshl_add_u64 v[10:11], v[8:9], 0, v[0:1]
	s_mov_b32 m0, s1
	v_readfirstlane_b32 s1, v156
	global_load_lds_dwordx4 v[10:11], off
	s_mov_b32 m0, s1
	s_add_u32 s10, s10, 0xb0000
	v_readlane_b32 s1, v254, 62
	v_lshl_add_u64 v[8:9], s[22:23], 0, v[18:19]
	s_addc_u32 s11, s11, 0
	v_add_u32_e32 v157, s1, v14
	v_lshl_add_u64 v[8:9], v[8:9], 0, v[2:3]
	v_lshl_add_u64 v[20:21], s[10:11], 0, v[16:17]
	v_readfirstlane_b32 s1, v157
	v_add_u32_e32 v158, 0x2000, v157
	global_load_lds_dwordx4 v[8:9], off
	v_lshl_add_u64 v[20:21], v[20:21], 0, v[0:1]
	s_mov_b32 m0, s1
	v_readfirstlane_b32 s1, v158
	global_load_lds_dwordx4 v[20:21], off
	s_mov_b32 m0, s1
	s_add_i32 s1, s20, 0x80
	v_lshl_add_u64 v[20:21], s[10:11], 0, v[18:19]
	s_mul_hi_i32 s10, s1, 0x1600
	s_add_i32 s1, s8, 0xb0000
	s_add_u32 s1, s66, s1
	s_addc_u32 s22, s67, s10
	s_add_u32 s10, s1, s68
	s_addc_u32 s11, s22, 0
	v_add_u32_e32 v160, 0x4000, v155
	v_lshl_add_u64 v[20:21], v[20:21], 0, v[2:3]
	v_lshl_add_u64 v[16:17], s[10:11], 0, v[16:17]
	v_readfirstlane_b32 s23, v160
	global_load_lds_dwordx4 v[20:21], off
	v_lshl_add_u64 v[16:17], v[16:17], 0, v[0:1]
	s_mov_b32 m0, s23
	v_add_u32_e32 v164, 0x6000, v155
	global_load_lds_dwordx4 v[16:17], off
	v_lshl_add_u64 v[16:17], s[10:11], 0, v[18:19]
	v_readfirstlane_b32 s10, v164
	v_lshl_add_u64 v[16:17], v[16:17], 0, v[2:3]
	s_mov_b32 m0, s10
	v_ashrrev_i32_e32 v15, 8, v144
	global_load_lds_dwordx4 v[16:17], off
	v_mov_b32_e32 v21, 0
	v_mov_b32_e32 v22, 0
	v_mov_b32_e32 v23, 0
	v_mov_b32_e32 v24, 0
	v_mov_b32_e32 v25, 0
	v_mov_b32_e32 v26, 0
	v_mov_b32_e32 v27, 0
	v_mov_b32_e32 v28, 0
	v_mov_b32_e32 v29, 0
	v_mov_b32_e32 v30, 0
	v_mov_b32_e32 v31, 0
	v_mov_b32_e32 v32, 0
	v_mov_b32_e32 v33, 0
	v_mov_b32_e32 v34, 0
	v_mov_b32_e32 v35, 0
	v_mov_b32_e32 v36, 0
	v_mov_b32_e32 v37, 0
	v_mov_b32_e32 v38, 0
	v_mov_b32_e32 v39, 0
	v_mov_b32_e32 v40, 0
	v_mov_b32_e32 v41, 0
	v_mov_b32_e32 v42, 0
	v_mov_b32_e32 v43, 0
	v_mov_b32_e32 v44, 0
	v_mov_b32_e32 v45, 0
	v_mov_b32_e32 v46, 0
	v_mov_b32_e32 v47, 0
	v_mov_b32_e32 v48, 0
	v_mov_b32_e32 v49, 0
	v_mov_b32_e32 v50, 0
	v_mov_b32_e32 v51, 0
	v_mov_b32_e32 v52, 0
	v_mov_b32_e32 v53, 0
	v_mov_b32_e32 v54, 0
	v_mov_b32_e32 v55, 0
	v_mov_b32_e32 v56, 0
	v_mov_b32_e32 v57, 0
	v_mov_b32_e32 v58, 0
	v_mov_b32_e32 v59, 0
	v_mov_b32_e32 v60, 0
	v_mov_b32_e32 v61, 0
	v_mov_b32_e32 v62, 0
	v_mov_b32_e32 v63, 0
	v_mov_b32_e32 v64, 0
	v_mov_b32_e32 v65, 0
	v_mov_b32_e32 v66, 0
	v_mov_b32_e32 v67, 0
	v_mov_b32_e32 v68, 0
	v_mov_b32_e32 v69, 0
	v_mov_b32_e32 v70, 0
	v_mov_b32_e32 v71, 0
	v_mov_b32_e32 v72, 0
	v_mov_b32_e32 v73, 0
	v_mov_b32_e32 v74, 0
	v_mov_b32_e32 v75, 0
	v_mov_b32_e32 v76, 0
	v_mov_b32_e32 v77, 0
	v_mov_b32_e32 v78, 0
	v_mov_b32_e32 v79, 0
	v_mov_b32_e32 v80, 0
	v_mov_b32_e32 v81, 0
	v_mov_b32_e32 v82, 0
	v_mov_b32_e32 v83, 0
	v_mov_b32_e32 v84, 0
	v_mov_b32_e32 v85, 0
	v_mov_b32_e32 v86, 0
	v_mov_b32_e32 v87, 0
	v_mov_b32_e32 v88, 0
	v_mov_b32_e32 v89, 0
	v_mov_b32_e32 v90, 0
	v_mov_b32_e32 v91, 0
	v_mov_b32_e32 v92, 0
	v_mov_b32_e32 v93, 0
	v_mov_b32_e32 v94, 0
	v_mov_b32_e32 v95, 0
	v_mov_b32_e32 v96, 0
	v_mov_b32_e32 v97, 0
	v_mov_b32_e32 v98, 0
	v_mov_b32_e32 v99, 0
	v_mov_b32_e32 v100, 0
	v_mov_b32_e32 v101, 0
	v_mov_b32_e32 v102, 0
	v_mov_b32_e32 v103, 0
	v_mov_b32_e32 v104, 0
	v_mov_b32_e32 v105, 0
	v_mov_b32_e32 v106, 0
	v_mov_b32_e32 v107, 0
	v_mov_b32_e32 v108, 0
	v_mov_b32_e32 v109, 0
	v_mov_b32_e32 v110, 0
	v_mov_b32_e32 v111, 0
	v_mov_b32_e32 v112, 0
	v_mov_b32_e32 v113, 0
	v_mov_b32_e32 v114, 0
	v_mov_b32_e32 v115, 0
	v_mov_b32_e32 v116, 0
	v_mov_b32_e32 v117, 0
	v_mov_b32_e32 v118, 0
	v_mov_b32_e32 v119, 0
	v_mov_b32_e32 v120, 0
	v_mov_b32_e32 v121, 0
	v_mov_b32_e32 v122, 0
	v_mov_b32_e32 v123, 0
	v_mov_b32_e32 v124, 0
	v_mov_b32_e32 v125, 0
	v_mov_b32_e32 v126, 0
	v_mov_b32_e32 v127, 0
	v_not_b32_e32 v162, 31
	v_not_b32_e32 v246, 63
	v_cmp_eq_u32_e32 vcc, 1, v15
	s_and_saveexec_b64 s[10:11], vcc
	s_cbranch_execz .LBB0_188
	s_barrier
.LBB0_188:
	s_or_b64 exec, exec, s[10:11]
	v_readlane_b32 s11, v254, 63
	s_mov_b64 s[24:25], 0x80
	v_lshl_add_u64 v[4:5], v[4:5], 0, s[24:25]
	v_add_u32_e32 v165, s11, v14
	v_add_u32_e32 v166, 0x2000, v165
	v_readfirstlane_b32 s10, v165
	s_mov_b32 m0, s10
	v_readfirstlane_b32 s10, v166
	v_add_u32_e32 v167, 0x8000, v155
	s_add_u32 s2, s2, s68
	s_waitcnt vmcnt(4)
	s_barrier
	global_load_lds_dwordx4 v[4:5], off
	v_lshl_add_u64 v[4:5], v[6:7], 0, s[24:25]
	s_mov_b32 m0, s10
	v_readfirstlane_b32 s10, v167
	v_add_u32_e32 v168, 0xa000, v155
	s_addc_u32 s3, s3, 0
	global_load_lds_dwordx4 v[4:5], off
	v_lshl_add_u64 v[4:5], v[10:11], 0, s[24:25]
	s_mov_b32 m0, s10
	v_readfirstlane_b32 s10, v168
	s_add_u32 s2, s2, 0xb0080
	v_readlane_b32 s23, v255, 0
	global_load_lds_dwordx4 v[4:5], off
	v_lshl_add_u64 v[4:5], v[8:9], 0, s[24:25]
	s_mov_b32 m0, s10
	s_addc_u32 s3, s3, 0
	v_add_u32_e32 v169, s23, v14
	global_load_lds_dwordx4 v[4:5], off
	v_lshl_add_u64 v[4:5], v[132:133], 1, s[2:3]
	v_readfirstlane_b32 s10, v169
	v_lshl_add_u64 v[4:5], v[4:5], 0, v[0:1]
	s_mov_b32 m0, s10
	v_add_u32_e32 v171, 0x2000, v169
	global_load_lds_dwordx4 v[4:5], off
	v_lshl_add_u64 v[4:5], v[134:135], 1, s[2:3]
	v_readfirstlane_b32 s2, v171
	v_lshl_add_u64 v[4:5], v[4:5], 0, v[2:3]
	s_mov_b32 m0, s2
	v_and_b32_e32 v16, 15, v144
	global_load_lds_dwordx4 v[4:5], off
	v_bfe_u32 v146, v144, 4, 2
	v_lshlrev_b32_e32 v6, 2, v144
	v_lshlrev_b32_e32 v4, 4, v146
	v_lshlrev_b32_e32 v5, 6, v16
	v_and_b32_e32 v6, 32, v6
	v_bitop3_b32 v5, v4, v6, v5 bitop3:0x36
	v_readlane_b32 s3, v254, 61
	v_add_u32_e32 v11, s11, v5
	v_add_u32_e32 v14, s23, v5
	v_add_u32_e32 v9, s3, v5
	v_readlane_b32 s3, v254, 62
	v_lshl_or_b32 v147, v15, 6, v16
	v_add_u32_e32 v16, 0, v5
	v_add_u32_e32 v10, s3, v5
	v_lshlrev_b32_e32 v5, 6, v144
	s_movk_i32 s3, 0x3c0
	v_and_or_b32 v4, v5, s3, v4
	v_xad_u32 v17, v4, v6, 0
	v_mov_b64_e32 v[4:5], s[4:5]
	s_movk_i32 s3, 0x1600
	v_mad_i64_i32 v[6:7], s[4:5], v13, s3, v[4:5]
	v_mad_i64_i32 v[4:5], s[4:5], v12, s3, v[4:5]
	v_lshl_add_u64 v[4:5], v[4:5], 0, v[0:1]
	v_lshl_add_u64 v[6:7], v[6:7], 0, v[2:3]
	v_lshl_add_u64 v[138:139], s[46:47], 0, v[4:5]
	v_mov_b64_e32 v[4:5], s[8:9]
	v_lshl_add_u64 v[136:137], s[46:47], 0, v[6:7]
	v_mad_i64_i32 v[6:7], s[4:5], v13, s3, v[4:5]
	v_lshl_add_u64 v[2:3], v[6:7], 0, v[2:3]
	v_lshl_add_u64 v[140:141], s[46:47], 0, v[2:3]
	v_mad_i64_i32 v[2:3], s[4:5], v12, s3, v[4:5]
	v_bfe_u32 v145, v144, 6, 2
	s_waitcnt vmcnt(6)
	v_lshlrev_b32_e32 v15, 13, v15
	v_lshl_add_u64 v[0:1], v[2:3], 0, v[0:1]
	v_lshlrev_b32_e32 v8, 12, v145
	v_or_b32_e32 v18, 0x800, v15
	v_or_b32_e32 v19, 0x1000, v15
	v_or_b32_e32 v20, 0x1800, v15
	v_lshl_add_u64 v[142:143], s[46:47], 0, v[0:1]
	v_mov_b32_e32 v0, 0
	s_add_i32 s2, s0, -2
	s_mov_b32 s3, 0
	v_add_u32_e32 v172, v9, v8
	v_add_u32_e32 v152, v16, v15
	v_add_u32_e32 v151, v17, v18
	v_add_u32_e32 v150, v17, v19
	v_add_u32_e32 v149, v17, v20
	v_add_u32_e32 v170, v10, v8
	v_add_u32_e32 v159, v11, v8
	v_add_u32_e32 v154, v14, v8
	v_mov_b32_e32 v1, v0
	v_mov_b32_e32 v2, v0
	v_mov_b32_e32 v3, v0
	v_mov_b32_e32 v4, v0
	v_mov_b32_e32 v5, v0
	v_mov_b32_e32 v6, v0
	v_mov_b32_e32 v7, v0
	v_mov_b32_e32 v8, v0
	v_mov_b32_e32 v9, v0
	v_mov_b32_e32 v10, v0
	v_mov_b32_e32 v11, v0
	v_mov_b32_e32 v12, v0
	v_mov_b32_e32 v13, v0
	v_mov_b32_e32 v14, v0
	v_mov_b32_e32 v15, v0
	v_mov_b32_e32 v16, v0
	v_mov_b32_e32 v17, v0
	v_mov_b32_e32 v18, v0
	v_mov_b32_e32 v19, v0
	v_mov_b32_e32 v20, v0
	s_waitcnt vmcnt(0)
	s_barrier

.LBB0_329:
	v_ashrrev_i32_e32 v0, 31, v140
	v_lshrrev_b32_e32 v0, 26, v0
	v_add_u32_e32 v0, v140, v0
	v_ashrrev_i32_e32 v1, 6, v0
	v_bfe_i32 v0, v140, 27, 1
	v_lshlrev_b32_e32 v21, 4, v140
	v_lshrrev_b32_e32 v0, 22, v0
	v_add_u32_e32 v0, v21, v0
	v_and_b32_e32 v0, 0xfffffc00, v0
	v_sub_u32_e32 v0, v21, v0
	v_lshrrev_b32_e32 v2, 4, v0
	v_bitop3_b32 v2, v2, v0, 32 bitop3:0x6c
	v_ashrrev_i32_e32 v0, 31, v0
	v_lshrrev_b32_e32 v0, 26, v0
	v_lshlrev_b32_e32 v3, 3, v1
	v_add_u32_e32 v0, v2, v0
	v_and_b32_e32 v3, -16, v3
	v_ashrrev_i32_e32 v4, 6, v0
	v_add_u32_e32 v0, v4, v3
	v_mul_i32_i24_e32 v3, 64, v4
	v_lshlrev_b32_e32 v1, 5, v1
	v_sub_u32_e32 v2, v2, v3
	v_mov_b32_e32 v7, 1
	v_and_b32_e32 v1, 32, v1
	v_ashrrev_i16_sdwa v2, v7, sext(v2) dst_sel:DWORD dst_unused:UNUSED_PAD src0_sel:DWORD src1_sel:BYTE_0
	v_add_u32_sdwa v2, v1, sext(v2) dst_sel:DWORD dst_unused:UNUSED_PAD src0_sel:DWORD src1_sel:WORD_0
	v_add_u32_e32 v1, 0x2000, v21
	v_ashrrev_i32_e32 v3, 31, v1
	v_lshrrev_b32_e32 v3, 22, v3
	v_add_u32_e32 v3, v1, v3
	v_ashrrev_i32_e32 v3, 10, v3
	v_mul_i32_i24_e32 v4, 0x400, v3
	v_sub_u32_e32 v1, v1, v4
	v_lshrrev_b32_e32 v4, 4, v1
	v_bitop3_b32 v1, v4, v1, 32 bitop3:0x6c
	s_add_i32 s0, s0, s1
	v_ashrrev_i32_e32 v5, 31, v1
	s_mul_hi_i32 s1, s0, 0x2e8ba2e9
	v_lshrrev_b32_e32 v5, 26, v5
	s_lshr_b32 s2, s1, 31
	s_ashr_i32 s1, s1, 4
	v_add_u32_e32 v5, v1, v5
	s_add_i32 s1, s1, s2
	v_ashrrev_i32_e32 v6, 6, v5
	v_and_b32_e32 v5, 0xc0, v5
	s_lshl_b32 s6, s1, 2
	v_lshlrev_b32_e32 v4, 3, v3
	v_lshlrev_b32_e32 v3, 5, v3
	v_sub_u32_e32 v1, v1, v5
	s_sub_i32 s2, 0x42, s6
	v_and_b32_e32 v4, -16, v4
	v_and_b32_e32 v3, 32, v3
	v_ashrrev_i16_sdwa v1, v7, sext(v1) dst_sel:DWORD dst_unused:UNUSED_PAD src0_sel:DWORD src1_sel:BYTE_0
	s_min_u32 s3, s2, 4
	s_mul_i32 s2, s1, 0x58
	v_add_u32_e32 v4, v6, v4
	v_add_u32_sdwa v6, v3, sext(v1) dst_sel:DWORD dst_unused:UNUSED_PAD src0_sel:DWORD src1_sel:WORD_0
	s_sub_i32 s7, s0, s2
	v_cvt_f32_ubyte0_e32 v3, s3
	v_cvt_f32_i32_e32 v1, s7
	v_rcp_iflag_f32_e32 v5, v3
	s_ashr_i32 s4, s7, 30
	s_or_b32 s8, s4, 1
	v_ashrrev_i32_e32 v7, 31, v6
	v_mul_f32_e32 v5, v1, v5
	v_trunc_f32_e32 v5, v5
	v_fma_f32 v1, -v5, v3, v1
	v_cvt_i32_f32_e32 v5, v5
	v_cmp_ge_f32_e64 s[4:5], |v1|, v3
	s_and_b64 s[4:5], s[4:5], exec
	s_cselect_b32 s4, s8, 0
	v_readfirstlane_b32 s5, v5
	s_add_i32 s4, s5, s4
	s_mul_i32 s3, s4, s3
	s_sext_i32_i8 s14, s4
	s_sub_i32 s4, s7, s3
	s_sext_i32_i8 s4, s4
	s_lshl_b32 s8, s14, 8
	s_add_i32 s6, s6, s4
	s_ashr_i32 s9, s8, 31
	s_lshl_b32 s4, s6, 8
	s_lshl_b64 s[6:7], s[8:9], 11
	s_add_u32 s16, s12, s6
	v_readlane_b32 s5, v254, 61
	v_ashrrev_i32_e32 v1, 31, v0
	s_addc_u32 s17, s13, s7
	v_add_u32_e32 v144, s5, v21
	v_lshlrev_b64 v[0:1], 11, v[0:1]
	v_ashrrev_i32_e32 v3, 31, v2
	v_lshl_add_u64 v[8:9], s[16:17], 0, v[0:1]
	v_lshlrev_b64 v[2:3], 1, v[2:3]
	v_readfirstlane_b32 s5, v144
	v_add_u32_e32 v149, 0x2000, v144
	v_lshl_add_u64 v[8:9], v[8:9], 0, v[2:3]
	s_mov_b32 m0, s5
	v_ashrrev_i32_e32 v5, 31, v4
	v_readfirstlane_b32 s5, v149
	global_load_lds_dwordx4 v[8:9], off
	v_lshlrev_b64 v[4:5], 11, v[4:5]
	s_mov_b32 m0, s5
	s_ashr_i32 s5, s4, 31
	v_lshl_add_u64 v[10:11], s[16:17], 0, v[4:5]
	s_lshl_b64 s[16:17], s[4:5], 11
	s_add_u32 s16, s44, s16
	s_addc_u32 s17, s45, s17
	s_bitset1_b32 s8, 7
	s_ashr_i32 s9, s8, 31
	s_lshl_b64 s[8:9], s[8:9], 11
	v_lshlrev_b64 v[6:7], 1, v[6:7]
	v_add_u32_e32 v150, 0, v21
	s_add_u32 s8, s12, s8
	v_lshl_add_u64 v[10:11], v[10:11], 0, v[6:7]
	v_lshl_add_u64 v[12:13], s[16:17], 0, v[0:1]
	v_readfirstlane_b32 s5, v150
	v_add_u32_e32 v151, 0x2000, v150
	s_addc_u32 s9, s13, s9
	global_load_lds_dwordx4 v[10:11], off
	v_lshl_add_u64 v[12:13], v[12:13], 0, v[2:3]
	s_mov_b32 m0, s5
	v_readfirstlane_b32 s5, v151
	v_lshl_add_u64 v[16:17], s[8:9], 0, v[0:1]
	v_lshl_add_u64 v[18:19], s[8:9], 0, v[4:5]
	s_or_b32 s8, s4, 0x80
	global_load_lds_dwordx4 v[12:13], off
	s_mov_b32 m0, s5
	v_readlane_b32 s5, v254, 62
	s_ashr_i32 s9, s8, 31
	v_lshl_add_u64 v[14:15], s[16:17], 0, v[4:5]
	v_add_u32_e32 v153, s5, v21
	s_lshl_b64 s[8:9], s[8:9], 11
	v_lshl_add_u64 v[14:15], v[14:15], 0, v[6:7]
	v_readfirstlane_b32 s5, v153
	v_add_u32_e32 v154, 0x2000, v153
	s_add_u32 s8, s44, s8
	global_load_lds_dwordx4 v[14:15], off
	v_lshl_add_u64 v[16:17], v[16:17], 0, v[2:3]
	s_mov_b32 m0, s5
	v_readfirstlane_b32 s5, v154
	s_addc_u32 s9, s45, s9
	v_add_u32_e32 v155, 0x4000, v150
	global_load_lds_dwordx4 v[16:17], off
	v_lshl_add_u64 v[18:19], v[18:19], 0, v[6:7]
	s_mov_b32 m0, s5
	v_lshl_add_u64 v[22:23], s[8:9], 0, v[0:1]
	v_readfirstlane_b32 s5, v155
	v_add_u32_e32 v157, 0x6000, v150
	global_load_lds_dwordx4 v[18:19], off
	v_lshl_add_u64 v[128:129], v[22:23], 0, v[2:3]
	s_mov_b32 m0, s5
	v_lshl_add_u64 v[22:23], s[8:9], 0, v[4:5]
	v_readfirstlane_b32 s5, v157
	global_load_lds_dwordx4 v[128:129], off
	v_lshl_add_u64 v[130:131], v[22:23], 0, v[6:7]
	s_mov_b32 m0, s5
	v_ashrrev_i32_e32 v20, 8, v140
	global_load_lds_dwordx4 v[130:131], off
	v_mov_b32_e32 v23, 0
	v_mov_b32_e32 v24, 0
	v_mov_b32_e32 v25, 0
	v_mov_b32_e32 v26, 0
	v_mov_b32_e32 v27, 0
	v_mov_b32_e32 v28, 0
	v_mov_b32_e32 v29, 0
	v_mov_b32_e32 v30, 0
	v_mov_b32_e32 v31, 0
	v_mov_b32_e32 v32, 0
	v_mov_b32_e32 v33, 0
	v_mov_b32_e32 v34, 0
	v_mov_b32_e32 v35, 0
	v_mov_b32_e32 v36, 0
	v_mov_b32_e32 v37, 0
	v_mov_b32_e32 v38, 0
	v_mov_b32_e32 v39, 0
	v_mov_b32_e32 v40, 0
	v_mov_b32_e32 v41, 0
	v_mov_b32_e32 v42, 0
	v_mov_b32_e32 v43, 0
	v_mov_b32_e32 v44, 0
	v_mov_b32_e32 v45, 0
	v_mov_b32_e32 v46, 0
	v_mov_b32_e32 v47, 0
	v_mov_b32_e32 v48, 0
	v_mov_b32_e32 v49, 0
	v_mov_b32_e32 v50, 0
	v_mov_b32_e32 v51, 0
	v_mov_b32_e32 v52, 0
	v_mov_b32_e32 v53, 0
	v_mov_b32_e32 v54, 0
	v_mov_b32_e32 v55, 0
	v_mov_b32_e32 v56, 0
	v_mov_b32_e32 v57, 0
	v_mov_b32_e32 v58, 0
	v_mov_b32_e32 v59, 0
	v_mov_b32_e32 v60, 0
	v_mov_b32_e32 v61, 0
	v_mov_b32_e32 v62, 0
	v_mov_b32_e32 v63, 0
	v_mov_b32_e32 v64, 0
	v_mov_b32_e32 v65, 0
	v_mov_b32_e32 v66, 0
	v_mov_b32_e32 v67, 0
	v_mov_b32_e32 v68, 0
	v_mov_b32_e32 v69, 0
	v_mov_b32_e32 v70, 0
	v_mov_b32_e32 v71, 0
	v_mov_b32_e32 v72, 0
	v_mov_b32_e32 v73, 0
	v_mov_b32_e32 v74, 0
	v_mov_b32_e32 v75, 0
	v_mov_b32_e32 v76, 0
	v_mov_b32_e32 v77, 0
	v_mov_b32_e32 v78, 0
	v_mov_b32_e32 v79, 0
	v_mov_b32_e32 v80, 0
	v_mov_b32_e32 v81, 0
	v_mov_b32_e32 v82, 0
	v_mov_b32_e32 v83, 0
	v_mov_b32_e32 v84, 0
	v_mov_b32_e32 v85, 0
	v_mov_b32_e32 v86, 0
	v_mov_b32_e32 v87, 0
	v_mov_b32_e32 v88, 0
	v_mov_b32_e32 v89, 0
	v_mov_b32_e32 v90, 0
	v_mov_b32_e32 v91, 0
	v_mov_b32_e32 v92, 0
	v_mov_b32_e32 v93, 0
	v_mov_b32_e32 v94, 0
	v_mov_b32_e32 v95, 0
	v_mov_b32_e32 v96, 0
	v_mov_b32_e32 v97, 0
	v_mov_b32_e32 v98, 0
	v_mov_b32_e32 v99, 0
	v_mov_b32_e32 v100, 0
	v_mov_b32_e32 v101, 0
	v_mov_b32_e32 v102, 0
	v_mov_b32_e32 v103, 0
	v_mov_b32_e32 v104, 0
	v_mov_b32_e32 v105, 0
	v_mov_b32_e32 v106, 0
	v_mov_b32_e32 v107, 0
	v_mov_b32_e32 v108, 0
	v_mov_b32_e32 v109, 0
	v_mov_b32_e32 v110, 0
	v_mov_b32_e32 v111, 0
	v_mov_b32_e32 v112, 0
	v_mov_b32_e32 v113, 0
	v_mov_b32_e32 v114, 0
	v_mov_b32_e32 v115, 0
	v_mov_b32_e32 v116, 0
	v_mov_b32_e32 v117, 0
	v_mov_b32_e32 v118, 0
	v_mov_b32_e32 v119, 0
	v_mov_b32_e32 v120, 0
	v_mov_b32_e32 v121, 0
	v_mov_b32_e32 v122, 0
	v_mov_b32_e32 v123, 0
	v_mov_b32_e32 v124, 0
	v_mov_b32_e32 v125, 0
	v_mov_b32_e32 v126, 0
	v_mov_b32_e32 v127, 0
	v_cmp_eq_u32_e32 vcc, 1, v20
	s_and_saveexec_b64 s[8:9], vcc
	s_cbranch_execz .LBB0_331
	s_barrier
.LBB0_331:
	s_or_b64 exec, exec, s[8:9]
	v_readlane_b32 s8, v254, 63
	s_mov_b64 s[16:17], 0x80
	v_lshl_add_u64 v[8:9], v[8:9], 0, s[16:17]
	v_add_u32_e32 v158, s8, v21
	v_add_u32_e32 v159, 0x2000, v158
	v_readfirstlane_b32 s5, v158
	s_mov_b32 m0, s5
	v_readfirstlane_b32 s5, v159
	v_add_u32_e32 v160, 0x8000, v150
	s_waitcnt vmcnt(4)
	s_barrier
	global_load_lds_dwordx4 v[8:9], off
	v_lshl_add_u64 v[8:9], v[10:11], 0, s[16:17]
	s_mov_b32 m0, s5
	v_readfirstlane_b32 s5, v160
	v_add_u32_e32 v164, 0xa000, v150
	v_readlane_b32 s9, v255, 0
	global_load_lds_dwordx4 v[8:9], off
	v_lshl_add_u64 v[8:9], v[12:13], 0, s[16:17]
	s_mov_b32 m0, s5
	v_readfirstlane_b32 s5, v164
	v_add_u32_e32 v165, s9, v21
	global_load_lds_dwordx4 v[8:9], off
	v_lshl_add_u64 v[8:9], v[14:15], 0, s[16:17]
	s_mov_b32 m0, s5
	v_readfirstlane_b32 s5, v165
	v_add_u32_e32 v166, 0x2000, v165
	global_load_lds_dwordx4 v[8:9], off
	v_lshl_add_u64 v[8:9], v[16:17], 0, s[16:17]
	s_mov_b32 m0, s5
	v_readfirstlane_b32 s5, v166
	global_load_lds_dwordx4 v[8:9], off
	v_lshl_add_u64 v[8:9], v[18:19], 0, s[16:17]
	s_mov_b32 m0, s5
	s_sub_i32 s0, s0, s3
	global_load_lds_dwordx4 v[8:9], off
	v_and_b32_e32 v22, 15, v140
	v_bfe_u32 v141, v140, 4, 2
	v_lshlrev_b32_e32 v11, 2, v140
	s_sub_i32 s0, s0, s2
	v_lshlrev_b32_e32 v8, 4, v141
	v_lshlrev_b32_e32 v9, 6, v22
	v_and_b32_e32 v11, 32, v11
	s_sext_i32_i8 s0, s0
	v_bitop3_b32 v9, v8, v11, v9 bitop3:0x36
	v_readlane_b32 s5, v254, 61
	s_lshl_b32 s1, s1, 10
	s_lshl_b32 s0, s0, 8
	v_add_u32_e32 v12, s5, v9
	v_readlane_b32 s5, v254, 62
	s_add_i32 s0, s1, s0
	v_add_u32_e32 v14, s8, v9
	v_add_u32_e32 v13, s5, v9
	v_add_u32_e32 v15, s9, v9
	v_add_u32_e32 v17, 0, v9
	v_lshlrev_b32_e32 v9, 6, v140
	s_movk_i32 s5, 0x3c0
	s_ashr_i32 s1, s0, 31
	v_and_or_b32 v8, v9, s5, v8
	s_lshl_b64 s[0:1], s[0:1], 11
	v_xad_u32 v11, v8, v11, 0
	v_lshl_add_u64 v[8:9], s[0:1], 0, v[4:5]
	v_lshl_add_u64 v[8:9], v[8:9], 0, v[6:7]
	v_lshl_add_u64 v[132:133], s[44:45], 0, v[8:9]
	v_lshl_add_u64 v[8:9], s[0:1], 0, v[0:1]
	v_lshl_add_u64 v[0:1], s[6:7], 0, v[0:1]
	v_bfe_u32 v142, v140, 6, 2
	s_waitcnt vmcnt(6)
	v_lshlrev_b32_e32 v16, 13, v20
	v_lshl_add_u64 v[4:5], s[6:7], 0, v[4:5]
	v_lshl_add_u64 v[0:1], v[0:1], 0, v[2:3]
	v_lshlrev_b32_e32 v10, 12, v142
	v_lshl_or_b32 v143, v20, 6, v22
	v_or_b32_e32 v18, 0x800, v16
	v_or_b32_e32 v19, 0x1000, v16
	v_or_b32_e32 v20, 0x1800, v16
	v_lshl_add_u64 v[8:9], v[8:9], 0, v[2:3]
	v_lshl_add_u64 v[4:5], v[4:5], 0, v[6:7]
	v_lshl_add_u64 v[138:139], s[46:47], 0, v[0:1]
	v_mov_b32_e32 v0, 0
	v_lshl_add_u64 v[134:135], s[44:45], 0, v[8:9]
	v_lshl_add_u64 v[136:137], s[46:47], 0, v[4:5]
	s_mov_b32 s0, -2
	s_mov_b64 s[6:7], 0
	v_add_u32_e32 v168, v12, v10
	v_add_u32_e32 v148, v17, v16
	v_add_u32_e32 v147, v11, v18
	v_add_u32_e32 v146, v11, v19
	v_add_u32_e32 v145, v11, v20
	v_add_u32_e32 v167, v13, v10
	v_add_u32_e32 v156, v14, v10
	v_add_u32_e32 v152, v15, v10
	v_mov_b32_e32 v1, v0
	v_mov_b32_e32 v2, v0
	v_mov_b32_e32 v3, v0
	v_mov_b32_e32 v4, v0
	v_mov_b32_e32 v5, v0
	v_mov_b32_e32 v6, v0
	v_mov_b32_e32 v7, v0
	v_mov_b32_e32 v8, v0
	v_mov_b32_e32 v9, v0
	v_mov_b32_e32 v10, v0
	v_mov_b32_e32 v11, v0
	v_mov_b32_e32 v12, v0
	v_mov_b32_e32 v13, v0
	v_mov_b32_e32 v14, v0
	v_mov_b32_e32 v15, v0
	v_mov_b32_e32 v16, v0
	v_mov_b32_e32 v17, v0
	v_mov_b32_e32 v18, v0
	v_mov_b32_e32 v19, v0
	v_mov_b32_e32 v20, v0
	v_mov_b32_e32 v21, v0
	v_mov_b32_e32 v22, v0
	s_barrier

.LBB0_357:
	v_bfe_i32 v1, v144, 27, 1
	v_lshlrev_b32_e32 v24, 4, v144
	v_lshrrev_b32_e32 v1, 22, v1
	v_add_u32_e32 v1, v24, v1
	v_and_b32_e32 v1, 0xfffffc00, v1
	v_ashrrev_i32_e32 v0, 31, v144
	v_sub_u32_e32 v1, v24, v1
	v_lshrrev_b32_e32 v0, 26, v0
	v_lshrrev_b32_e32 v2, 4, v1
	v_add_u32_e32 v0, v144, v0
	v_bitop3_b32 v2, v2, v1, 32 bitop3:0x6c
	v_ashrrev_i32_e32 v1, 31, v1
	v_ashrrev_i32_e32 v0, 6, v0
	v_lshrrev_b32_e32 v1, 26, v1
	v_lshlrev_b32_e32 v3, 3, v0
	v_add_u32_e32 v1, v2, v1
	v_and_b32_e32 v3, -16, v3
	v_ashrrev_i32_e32 v1, 6, v1
	s_waitcnt vmcnt(0)
	v_add_u32_e32 v8, v1, v3
	v_mul_i32_i24_e32 v1, 64, v1
	v_lshlrev_b32_e32 v0, 5, v0
	v_sub_u32_e32 v1, v2, v1
	v_mov_b32_e32 v5, 1
	v_and_b32_e32 v0, 32, v0
	v_ashrrev_i16_sdwa v1, v5, sext(v1) dst_sel:DWORD dst_unused:UNUSED_PAD src0_sel:DWORD src1_sel:BYTE_0
	v_add_u32_sdwa v128, v0, sext(v1) dst_sel:DWORD dst_unused:UNUSED_PAD src0_sel:DWORD src1_sel:WORD_0
	v_add_u32_e32 v0, 0x2000, v24
	v_ashrrev_i32_e32 v1, 31, v0
	v_lshrrev_b32_e32 v1, 22, v1
	v_add_u32_e32 v1, v0, v1
	v_ashrrev_i32_e32 v1, 10, v1
	v_mul_i32_i24_e32 v2, 0x400, v1
	v_sub_u32_e32 v0, v0, v2
	v_lshrrev_b32_e32 v2, 4, v0
	v_bitop3_b32 v0, v2, v0, 32 bitop3:0x6c
	v_ashrrev_i32_e32 v3, 31, v0
	v_lshrrev_b32_e32 v3, 26, v3
	s_lshl_b32 s10, s1, 8
	v_lshlrev_b32_e32 v2, 3, v1
	v_add_u32_e32 v3, v0, v3
	s_ashr_i32 s11, s10, 31
	v_and_b32_e32 v2, -16, v2
	v_ashrrev_i32_e32 v4, 6, v3
	s_lshl_b64 s[12:13], s[10:11], 11
	v_add_u32_e32 v10, v4, v2
	v_and_b32_e32 v2, 0xc0, v3
	s_add_u32 s1, s26, s12
	v_lshlrev_b32_e32 v1, 5, v1
	v_sub_u32_e32 v0, v0, v2
	s_addc_u32 s3, s27, s13
	s_lshl_b32 s68, s14, 1
	v_and_b32_e32 v1, 32, v1
	v_ashrrev_i16_sdwa v0, v5, sext(v0) dst_sel:DWORD dst_unused:UNUSED_PAD src0_sel:DWORD src1_sel:BYTE_0
	s_add_u32 s2, s1, s68
	v_readlane_b32 s1, v254, 61
	v_ashrrev_i32_e32 v9, 31, v8
	v_add_u32_sdwa v130, v1, sext(v0) dst_sel:DWORD dst_unused:UNUSED_PAD src0_sel:DWORD src1_sel:WORD_0
	s_addc_u32 s3, s3, 0
	v_add_u32_e32 v152, s1, v24
	v_lshlrev_b64 v[0:1], 11, v[8:9]
	v_ashrrev_i32_e32 v129, 31, v128
	v_lshl_add_u64 v[4:5], s[2:3], 0, v[0:1]
	v_lshlrev_b64 v[2:3], 1, v[128:129]
	v_readfirstlane_b32 s1, v152
	v_add_u32_e32 v153, 0x2000, v152
	s_ashr_i32 s5, s4, 31
	v_lshl_add_u64 v[12:13], v[4:5], 0, v[2:3]
	s_mov_b32 m0, s1
	v_readfirstlane_b32 s1, v153
	s_lshl_b64 s[14:15], s[4:5], 11
	global_load_lds_dwordx4 v[12:13], off
	v_ashrrev_i32_e32 v11, 31, v10
	s_mov_b32 m0, s1
	s_add_u32 s1, s44, s14
	v_lshlrev_b64 v[4:5], 11, v[10:11]
	s_addc_u32 s5, s45, s15
	v_lshl_add_u64 v[14:15], s[2:3], 0, v[4:5]
	v_ashrrev_i32_e32 v131, 31, v130
	s_add_u32 s2, s1, s68
	v_lshlrev_b64 v[6:7], 1, v[130:131]
	s_addc_u32 s3, s5, 0
	v_add_u32_e32 v155, 0, v24
	v_lshl_add_u64 v[14:15], v[14:15], 0, v[6:7]
	v_lshl_add_u64 v[16:17], s[2:3], 0, v[0:1]
	v_readfirstlane_b32 s11, v155
	v_add_u32_e32 v156, 0x2000, v155
	global_load_lds_dwordx4 v[14:15], off
	v_lshl_add_u64 v[16:17], v[16:17], 0, v[2:3]
	s_mov_b32 m0, s11
	v_lshl_add_u64 v[18:19], s[2:3], 0, v[4:5]
	v_readfirstlane_b32 s2, v156
	global_load_lds_dwordx4 v[16:17], off
	s_mov_b32 m0, s2
	s_or_b32 s2, s10, 0x80
	s_ashr_i32 s3, s2, 31
	s_lshl_b64 s[2:3], s[2:3], 11
	s_add_u32 s2, s26, s2
	s_addc_u32 s3, s27, s3
	s_add_u32 s2, s2, s68
	v_readlane_b32 s11, v254, 62
	s_addc_u32 s3, s3, 0
	v_lshl_add_u64 v[18:19], v[18:19], 0, v[6:7]
	v_add_u32_e32 v158, s11, v24
	v_lshl_add_u64 v[20:21], s[2:3], 0, v[0:1]
	v_readfirstlane_b32 s11, v158
	v_add_u32_e32 v159, 0x2000, v158
	s_add_u32 s1, s1, 0x40000
	global_load_lds_dwordx4 v[18:19], off
	v_lshl_add_u64 v[20:21], v[20:21], 0, v[2:3]
	s_mov_b32 m0, s11
	v_lshl_add_u64 v[22:23], s[2:3], 0, v[4:5]
	v_readfirstlane_b32 s2, v159
	s_addc_u32 s5, s5, 0
	global_load_lds_dwordx4 v[20:21], off
	s_mov_b32 m0, s2
	s_add_u32 s2, s1, s68
	s_addc_u32 s3, s5, 0
	v_add_u32_e32 v160, 0x4000, v155
	v_lshl_add_u64 v[22:23], v[22:23], 0, v[6:7]
	v_lshl_add_u64 v[26:27], s[2:3], 0, v[0:1]
	v_readfirstlane_b32 s11, v160
	global_load_lds_dwordx4 v[22:23], off
	v_lshl_add_u64 v[26:27], v[26:27], 0, v[2:3]
	s_mov_b32 m0, s11
	v_add_u32_e32 v164, 0x6000, v155
	global_load_lds_dwordx4 v[26:27], off
	v_lshl_add_u64 v[26:27], s[2:3], 0, v[4:5]
	v_readfirstlane_b32 s2, v164
	v_lshl_add_u64 v[26:27], v[26:27], 0, v[6:7]
	s_mov_b32 m0, s2
	v_ashrrev_i32_e32 v25, 8, v144
	global_load_lds_dwordx4 v[26:27], off
	v_mov_b32_e32 v26, 0
	v_mov_b32_e32 v27, 0
	v_mov_b32_e32 v28, 0
	v_mov_b32_e32 v29, 0
	v_mov_b32_e32 v30, 0
	v_mov_b32_e32 v31, 0
	v_mov_b32_e32 v32, 0
	v_mov_b32_e32 v33, 0
	v_mov_b32_e32 v34, 0
	v_mov_b32_e32 v35, 0
	v_mov_b32_e32 v36, 0
	v_mov_b32_e32 v37, 0
	v_mov_b32_e32 v38, 0
	v_mov_b32_e32 v39, 0
	v_mov_b32_e32 v40, 0
	v_mov_b32_e32 v41, 0
	v_mov_b32_e32 v42, 0
	v_mov_b32_e32 v43, 0
	v_mov_b32_e32 v44, 0
	v_mov_b32_e32 v45, 0
	v_mov_b32_e32 v46, 0
	v_mov_b32_e32 v47, 0
	v_mov_b32_e32 v48, 0
	v_mov_b32_e32 v49, 0
	v_mov_b32_e32 v50, 0
	v_mov_b32_e32 v51, 0
	v_mov_b32_e32 v52, 0
	v_mov_b32_e32 v53, 0
	v_mov_b32_e32 v54, 0
	v_mov_b32_e32 v55, 0
	v_mov_b32_e32 v56, 0
	v_mov_b32_e32 v57, 0
	v_mov_b32_e32 v58, 0
	v_mov_b32_e32 v59, 0
	v_mov_b32_e32 v60, 0
	v_mov_b32_e32 v61, 0
	v_mov_b32_e32 v62, 0
	v_mov_b32_e32 v63, 0
	v_mov_b32_e32 v64, 0
	v_mov_b32_e32 v65, 0
	v_mov_b32_e32 v66, 0
	v_mov_b32_e32 v67, 0
	v_mov_b32_e32 v68, 0
	v_mov_b32_e32 v69, 0
	v_mov_b32_e32 v70, 0
	v_mov_b32_e32 v71, 0
	v_mov_b32_e32 v72, 0
	v_mov_b32_e32 v73, 0
	v_mov_b32_e32 v74, 0
	v_mov_b32_e32 v75, 0
	v_mov_b32_e32 v76, 0
	v_mov_b32_e32 v77, 0
	v_mov_b32_e32 v78, 0
	v_mov_b32_e32 v79, 0
	v_mov_b32_e32 v80, 0
	v_mov_b32_e32 v81, 0
	v_mov_b32_e32 v82, 0
	v_mov_b32_e32 v83, 0
	v_mov_b32_e32 v84, 0
	v_mov_b32_e32 v85, 0
	v_mov_b32_e32 v86, 0
	v_mov_b32_e32 v87, 0
	v_mov_b32_e32 v88, 0
	v_mov_b32_e32 v89, 0
	v_mov_b32_e32 v90, 0
	v_mov_b32_e32 v91, 0
	v_mov_b32_e32 v92, 0
	v_mov_b32_e32 v93, 0
	v_mov_b32_e32 v94, 0
	v_mov_b32_e32 v95, 0
	v_mov_b32_e32 v96, 0
	v_mov_b32_e32 v97, 0
	v_mov_b32_e32 v98, 0
	v_mov_b32_e32 v99, 0
	v_mov_b32_e32 v100, 0
	v_mov_b32_e32 v101, 0
	v_mov_b32_e32 v102, 0
	v_mov_b32_e32 v103, 0
	v_mov_b32_e32 v104, 0
	v_mov_b32_e32 v105, 0
	v_mov_b32_e32 v106, 0
	v_mov_b32_e32 v107, 0
	v_mov_b32_e32 v108, 0
	v_mov_b32_e32 v109, 0
	v_mov_b32_e32 v110, 0
	v_mov_b32_e32 v111, 0
	v_mov_b32_e32 v112, 0
	v_mov_b32_e32 v113, 0
	v_mov_b32_e32 v114, 0
	v_mov_b32_e32 v115, 0
	v_mov_b32_e32 v116, 0
	v_mov_b32_e32 v117, 0
	v_mov_b32_e32 v118, 0
	v_mov_b32_e32 v119, 0
	v_mov_b32_e32 v120, 0
	v_mov_b32_e32 v121, 0
	v_mov_b32_e32 v122, 0
	v_mov_b32_e32 v123, 0
	v_mov_b32_e32 v124, 0
	v_mov_b32_e32 v125, 0
	v_mov_b32_e32 v126, 0
	v_mov_b32_e32 v127, 0
	v_not_b32_e32 v246, 63
	v_cmp_eq_u32_e32 vcc, 1, v25
	s_and_saveexec_b64 s[20:21], vcc
	s_cbranch_execz .LBB0_359
	s_barrier
.LBB0_359:
	s_or_b64 exec, exec, s[20:21]
	v_readlane_b32 s11, v254, 63
	s_mov_b64 s[34:35], 0x80
	v_lshlrev_b64 v[134:135], 10, v[8:9]
	v_add_u32_e32 v165, s11, v24
	v_add_u32_e32 v166, 0x2000, v165
	v_readfirstlane_b32 s2, v165
	v_lshl_add_u64 v[8:9], v[12:13], 0, s[34:35]
	s_mov_b32 m0, s2
	v_readfirstlane_b32 s2, v166
	v_add_u32_e32 v167, 0x8000, v155
	s_waitcnt vmcnt(4)
	s_barrier
	global_load_lds_dwordx4 v[8:9], off
	v_lshl_add_u64 v[8:9], v[14:15], 0, s[34:35]
	s_mov_b32 m0, s2
	v_readfirstlane_b32 s2, v167
	v_add_u32_e32 v168, 0xa000, v155
	v_readlane_b32 s20, v255, 0
	global_load_lds_dwordx4 v[8:9], off
	v_lshl_add_u64 v[8:9], v[16:17], 0, s[34:35]
	s_mov_b32 m0, s2
	v_readfirstlane_b32 s2, v168
	v_add_u32_e32 v170, s20, v24
	global_load_lds_dwordx4 v[8:9], off
	v_lshl_add_u64 v[8:9], v[18:19], 0, s[34:35]
	s_mov_b32 m0, s2
	v_readfirstlane_b32 s2, v170
	v_add_u32_e32 v171, 0x2000, v170
	global_load_lds_dwordx4 v[8:9], off
	v_lshl_add_u64 v[8:9], v[20:21], 0, s[34:35]
	s_mov_b32 m0, s2
	v_readfirstlane_b32 s2, v171
	global_load_lds_dwordx4 v[8:9], off
	v_lshl_add_u64 v[8:9], v[22:23], 0, s[34:35]
	s_mov_b32 m0, s2
	v_lshlrev_b64 v[132:133], 10, v[10:11]
	global_load_lds_dwordx4 v[8:9], off
	v_and_b32_e32 v10, 15, v144
	v_bfe_u32 v146, v144, 4, 2
	v_lshlrev_b32_e32 v12, 2, v144
	v_lshlrev_b32_e32 v8, 4, v146
	v_lshlrev_b32_e32 v9, 6, v10
	v_and_b32_e32 v12, 32, v12
	v_bitop3_b32 v9, v8, v12, v9 bitop3:0x36
	v_readlane_b32 s3, v254, 61
	v_add_u32_e32 v15, s11, v9
	v_add_u32_e32 v16, s20, v9
	v_add_u32_e32 v13, s3, v9
	v_readlane_b32 s3, v254, 62
	v_add_u32_e32 v17, 0, v9
	v_bfe_u32 v145, v144, 6, 2
	v_add_u32_e32 v14, s3, v9
	v_lshlrev_b32_e32 v9, 6, v144
	s_movk_i32 s3, 0x3c0
	v_and_or_b32 v8, v9, s3, v8
	v_xad_u32 v12, v8, v12, 0
	v_lshl_add_u64 v[8:9], s[12:13], 0, v[4:5]
	v_lshl_add_u64 v[8:9], v[8:9], 0, v[6:7]
	v_lshl_add_u64 v[136:137], s[46:47], 0, v[8:9]
	v_lshl_add_u64 v[8:9], s[12:13], 0, v[0:1]
	v_lshl_add_u64 v[0:1], s[14:15], 0, v[0:1]
	s_waitcnt vmcnt(6)
	v_lshl_or_b32 v147, v25, 6, v10
	v_lshlrev_b32_e32 v10, 13, v25
	v_lshl_add_u64 v[4:5], s[14:15], 0, v[4:5]
	v_lshl_add_u64 v[0:1], v[0:1], 0, v[2:3]
	v_lshlrev_b32_e32 v11, 12, v145
	v_or_b32_e32 v18, 0x800, v10
	v_or_b32_e32 v19, 0x1000, v10
	v_or_b32_e32 v20, 0x1800, v10
	v_lshl_add_u64 v[8:9], v[8:9], 0, v[2:3]
	v_lshl_add_u64 v[4:5], v[4:5], 0, v[6:7]
	v_lshl_add_u64 v[142:143], s[44:45], 0, v[0:1]
	v_mov_b32_e32 v0, 0
	s_add_i32 s2, s0, -2
	v_lshl_add_u64 v[138:139], s[46:47], 0, v[8:9]
	v_lshl_add_u64 v[140:141], s[44:45], 0, v[4:5]
	s_mov_b32 s3, 0
	v_add_u32_e32 v172, v13, v11
	v_add_u32_e32 v151, v17, v10
	v_add_u32_e32 v150, v12, v18
	v_add_u32_e32 v149, v12, v19
	v_add_u32_e32 v148, v12, v20
	v_add_u32_e32 v169, v14, v11
	v_add_u32_e32 v157, v15, v11
	v_add_u32_e32 v154, v16, v11
	v_mov_b32_e32 v1, v0
	v_mov_b32_e32 v2, v0
	v_mov_b32_e32 v3, v0
	v_mov_b32_e32 v4, v0
	v_mov_b32_e32 v5, v0
	v_mov_b32_e32 v6, v0
	v_mov_b32_e32 v7, v0
	v_mov_b32_e32 v8, v0
	v_mov_b32_e32 v9, v0
	v_mov_b32_e32 v10, v0
	v_mov_b32_e32 v11, v0
	v_mov_b32_e32 v12, v0
	v_mov_b32_e32 v13, v0
	v_mov_b32_e32 v14, v0
	v_mov_b32_e32 v15, v0
	v_mov_b32_e32 v16, v0
	v_mov_b32_e32 v17, v0
	v_mov_b32_e32 v18, v0
	v_mov_b32_e32 v19, v0
	v_mov_b32_e32 v20, v0
	v_mov_b32_e32 v21, v0
	v_mov_b32_e32 v22, v0
	v_mov_b32_e32 v23, v0
	v_mov_b32_e32 v24, v0
	v_mov_b32_e32 v25, v0
	s_mov_b64 s[12:13], 0x880100
	s_mov_b64 s[14:15], 0x8c0100
	s_mov_b64 s[20:21], 0x880180
	s_mov_b64 s[34:35], 0x8c0180
	s_barrier

.LBB0_544:
	v_lshl_or_b32 v64, s0, 7, v147
	v_lshlrev_b32_e32 v251, 2, v64
	v_add_u32_e32 v64, s73, v251
	s_mul_i32 s1, s0, 0x2400
	ds_read_b32 v252, v64
	v_add_u32_e32 v64, s60, v251
	v_add_u32_e32 v156, s1, v160
	ds_read_b32 v146, v64
	ds_read_b128 v[80:83], v156 offset:58880
	ds_read_b128 v[64:67], v156 offset:54272
	ds_read_b128 v[148:151], v156 offset:54304
	ds_read_b128 v[152:155], v156 offset:58912
	s_waitcnt lgkmcnt(2)
	v_mfma_f32_32x32x16_bf16 v[64:79], v[64:67], v[96:99], 0
	s_lshl_b32 s0, s0, 9
	s_add_i32 s14, s57, s0
	s_or_b64 s[0:1], s[52:53], s[8:9]
	v_mov_b32_e32 v240, v147
	s_andn2_b64 vcc, exec, s[0:1]
	v_mfma_f32_32x32x16_bf16 v[80:95], v[80:83], v[96:99], 0
	s_waitcnt lgkmcnt(1)
	v_mfma_f32_32x32x16_bf16 v[64:79], v[148:151], v[100:103], v[64:79]
	s_waitcnt lgkmcnt(0)
	v_mfma_f32_32x32x16_bf16 v[80:95], v[152:155], v[100:103], v[80:95]
	ds_read_b128 v[148:151], v156 offset:54336
	ds_read_b128 v[152:155], v156 offset:58944
	s_waitcnt lgkmcnt(1)
	v_mfma_f32_32x32x16_bf16 v[64:79], v[148:151], v[104:107], v[64:79]
	s_waitcnt lgkmcnt(0)
	v_mfma_f32_32x32x16_bf16 v[80:95], v[152:155], v[104:107], v[80:95]
	ds_read_b128 v[148:151], v156 offset:54368
	ds_read_b128 v[152:155], v156 offset:58976
	s_waitcnt lgkmcnt(1)
	v_mfma_f32_32x32x16_bf16 v[64:79], v[148:151], v[108:111], v[64:79]
	s_waitcnt lgkmcnt(0)
	v_mfma_f32_32x32x16_bf16 v[80:95], v[152:155], v[108:111], v[80:95]
	s_nop 9
	v_mul_f32_e64 v64, v146, v64
	v_mul_f32_e64 v65, v146, v65
	v_mul_f32_e64 v78, v146, v78
	v_mul_f32_e64 v79, v146, v79
	v_mul_f32_e64 v76, v146, v76
	v_mul_f32_e64 v77, v146, v77
	v_pk_mul_f32 v[74:75], v[146:147], v[74:75] op_sel_hi:[0,1]
	v_pk_mul_f32 v[72:73], v[146:147], v[72:73] op_sel_hi:[0,1]
	v_pk_mul_f32 v[70:71], v[146:147], v[70:71] op_sel_hi:[0,1]
	v_pk_mul_f32 v[68:69], v[146:147], v[68:69] op_sel_hi:[0,1]
	v_pk_mul_f32 v[66:67], v[146:147], v[66:67] op_sel_hi:[0,1]
	v_pk_mul_f32 v[80:81], v[146:147], v[80:81] op_sel_hi:[0,1]
	v_pk_mul_f32 v[94:95], v[146:147], v[94:95] op_sel_hi:[0,1]
	v_pk_mul_f32 v[92:93], v[146:147], v[92:93] op_sel_hi:[0,1]
	v_pk_mul_f32 v[90:91], v[146:147], v[90:91] op_sel_hi:[0,1]
	v_pk_mul_f32 v[88:89], v[146:147], v[88:89] op_sel_hi:[0,1]
	v_pk_mul_f32 v[86:87], v[146:147], v[86:87] op_sel_hi:[0,1]
	v_pk_mul_f32 v[84:85], v[146:147], v[84:85] op_sel_hi:[0,1]
	v_pk_mul_f32 v[82:83], v[146:147], v[82:83] op_sel_hi:[0,1]
	s_cbranch_vccnz .LBB0_582
	s_andn2_b64 vcc, exec, s[2:3]
	s_mov_b64 s[10:11], -1
	v_lshl_add_u32 v164, v168, 2, s14
	ds_read_b128 v[148:151], v164
	ds_read_b128 v[152:155], v164 offset:32
	ds_read_b128 v[156:159], v164 offset:64
	ds_read_b128 v[164:167], v164 offset:96
	s_waitcnt lgkmcnt(3)
	v_add_f32_e32 v148, v252, v148
	v_add_f32_e32 v149, v252, v149
	v_add_f32_e32 v150, v252, v150
	v_add_f32_e32 v151, v252, v151
	s_waitcnt lgkmcnt(2)
	v_add_f32_e32 v152, v252, v152
	v_add_f32_e32 v153, v252, v153
	v_add_f32_e32 v154, v252, v154
	v_add_f32_e32 v155, v252, v155
	s_waitcnt lgkmcnt(1)
	v_add_f32_e32 v156, v252, v156
	v_add_f32_e32 v157, v252, v157
	v_add_f32_e32 v158, v252, v158
	v_add_f32_e32 v159, v252, v159
	s_waitcnt lgkmcnt(0)
	v_add_f32_e32 v164, v252, v164
	v_add_f32_e32 v165, v252, v165
	v_add_f32_e32 v166, v252, v166
	v_add_f32_e32 v167, v252, v167
	v_mul_f32_e32 v148, 0x3fb8aa3b, v148
	v_mul_f32_e32 v149, 0x3fb8aa3b, v149
	v_mul_f32_e32 v150, 0x3fb8aa3b, v150
	v_mul_f32_e32 v151, 0x3fb8aa3b, v151
	v_mul_f32_e32 v152, 0x3fb8aa3b, v152
	v_mul_f32_e32 v153, 0x3fb8aa3b, v153
	v_mul_f32_e32 v154, 0x3fb8aa3b, v154
	v_mul_f32_e32 v155, 0x3fb8aa3b, v155
	v_mul_f32_e32 v156, 0x3fb8aa3b, v156
	v_mul_f32_e32 v157, 0x3fb8aa3b, v157
	v_mul_f32_e32 v158, 0x3fb8aa3b, v158
	v_mul_f32_e32 v159, 0x3fb8aa3b, v159
	v_mul_f32_e32 v164, 0x3fb8aa3b, v164
	v_mul_f32_e32 v165, 0x3fb8aa3b, v165
	v_mul_f32_e32 v166, 0x3fb8aa3b, v166
	v_mul_f32_e32 v167, 0x3fb8aa3b, v167
	v_exp_f32_e32 v148, v148
	v_exp_f32_e32 v149, v149
	v_exp_f32_e32 v150, v150
	v_exp_f32_e32 v151, v151
	v_exp_f32_e32 v152, v152
	v_exp_f32_e32 v153, v153
	v_exp_f32_e32 v154, v154
	v_exp_f32_e32 v155, v155
	v_exp_f32_e32 v156, v156
	v_exp_f32_e32 v157, v157
	v_exp_f32_e32 v158, v158
	v_exp_f32_e32 v159, v159
	v_exp_f32_e32 v164, v164
	v_exp_f32_e32 v165, v165
	v_exp_f32_e32 v166, v166
	v_exp_f32_e32 v167, v167
	v_pk_mul_f32 v[148:149], v[0:1], v[148:149]
	v_pk_mul_f32 v[150:151], v[2:3], v[150:151]
	v_pk_mul_f32 v[152:153], v[4:5], v[152:153]
	v_pk_mul_f32 v[154:155], v[6:7], v[154:155]
	v_pk_mul_f32 v[156:157], v[8:9], v[156:157]
	v_pk_mul_f32 v[158:159], v[10:11], v[158:159]
	v_pk_mul_f32 v[164:165], v[12:13], v[164:165]
	v_pk_mul_f32 v[166:167], v[14:15], v[166:167]
.LBB0_547:
	s_and_b64 vcc, exec, s[2:3]
	s_cbranch_vccnz .LBB0_581
	v_sub_u32_e32 v232, v240, v168
	s_and_b64 vcc, exec, s[8:9]
	s_cbranch_vccz .Lp5_ge_0
	v_cmp_le_i32_e32 vcc, 0, v232
	v_cmp_le_i32_e64 s[0:1], 1, v232
	v_cmp_le_i32_e64 s[98:99], 2, v232
	v_cndmask_b32_e64 v148, 0, v148, vcc
	v_cndmask_b32_e64 v149, 0, v149, s[0:1]
	v_cndmask_b32_e64 v150, 0, v150, s[98:99]
	v_cmp_le_i32_e32 vcc, 3, v232
	v_cmp_le_i32_e64 s[0:1], 8, v232
	v_cmp_le_i32_e64 s[98:99], 9, v232
	v_cndmask_b32_e64 v151, 0, v151, vcc
	v_cndmask_b32_e64 v152, 0, v152, s[0:1]
	v_cndmask_b32_e64 v153, 0, v153, s[98:99]
	v_cmp_le_i32_e32 vcc, 10, v232
	v_cmp_le_i32_e64 s[0:1], 11, v232
	v_cmp_le_i32_e64 s[98:99], 16, v232
	v_cndmask_b32_e64 v154, 0, v154, vcc
	v_cndmask_b32_e64 v155, 0, v155, s[0:1]
	v_cndmask_b32_e64 v156, 0, v156, s[98:99]
	v_cmp_le_i32_e32 vcc, 17, v232
	v_cmp_le_i32_e64 s[0:1], 18, v232
	v_cmp_le_i32_e64 s[98:99], 19, v232
	v_cndmask_b32_e64 v157, 0, v157, vcc
	v_cndmask_b32_e64 v158, 0, v158, s[0:1]
	v_cndmask_b32_e64 v159, 0, v159, s[98:99]
	v_cmp_le_i32_e32 vcc, 24, v232
	v_cmp_le_i32_e64 s[0:1], 25, v232
	v_cmp_le_i32_e64 s[98:99], 26, v232
	v_cndmask_b32_e64 v164, 0, v164, vcc
	v_cndmask_b32_e64 v165, 0, v165, s[0:1]
	v_cndmask_b32_e64 v166, 0, v166, s[98:99]
	v_cmp_le_i32_e32 vcc, 27, v232
	s_nop 1
	v_cndmask_b32_e64 v167, 0, v167, vcc
	s_branch .LBB0_581
.Lp5_ge_0:
	v_cmp_ge_i32_e32 vcc, 0, v232
	v_cmp_ge_i32_e64 s[0:1], 1, v232
	v_cmp_ge_i32_e64 s[98:99], 2, v232
	v_cndmask_b32_e64 v148, 0, v148, vcc
	v_cndmask_b32_e64 v149, 0, v149, s[0:1]
	v_cndmask_b32_e64 v150, 0, v150, s[98:99]
	v_cmp_ge_i32_e32 vcc, 3, v232
	v_cmp_ge_i32_e64 s[0:1], 8, v232
	v_cmp_ge_i32_e64 s[98:99], 9, v232
	v_cndmask_b32_e64 v151, 0, v151, vcc
	v_cndmask_b32_e64 v152, 0, v152, s[0:1]
	v_cndmask_b32_e64 v153, 0, v153, s[98:99]
	v_cmp_ge_i32_e32 vcc, 10, v232
	v_cmp_ge_i32_e64 s[0:1], 11, v232
	v_cmp_ge_i32_e64 s[98:99], 16, v232
	v_cndmask_b32_e64 v154, 0, v154, vcc
	v_cndmask_b32_e64 v155, 0, v155, s[0:1]
	v_cndmask_b32_e64 v156, 0, v156, s[98:99]
	v_cmp_ge_i32_e32 vcc, 17, v232
	v_cmp_ge_i32_e64 s[0:1], 18, v232
	v_cmp_ge_i32_e64 s[98:99], 19, v232
	v_cndmask_b32_e64 v157, 0, v157, vcc
	v_cndmask_b32_e64 v158, 0, v158, s[0:1]
	v_cndmask_b32_e64 v159, 0, v159, s[98:99]
	v_cmp_ge_i32_e32 vcc, 24, v232
	v_cmp_ge_i32_e64 s[0:1], 25, v232
	v_cmp_ge_i32_e64 s[98:99], 26, v232
	v_cndmask_b32_e64 v164, 0, v164, vcc
	v_cndmask_b32_e64 v165, 0, v165, s[0:1]
	v_cndmask_b32_e64 v166, 0, v166, s[98:99]
	v_cmp_ge_i32_e32 vcc, 27, v232
	s_nop 1
	v_cndmask_b32_e64 v167, 0, v167, vcc

.LBB0_583:
	v_cndmask_b32_e64 v148, 0, 1, s[92:93]
	v_cndmask_b32_e64 v149, 0, 1, s[52:53]
	v_cndmask_b32_e64 v148, v148, v149, s[8:9]
	v_and_b32_e32 v148, 1, v148
	v_cmp_eq_u32_e32 vcc, 1, v148
	s_xor_b64 s[10:11], s[8:9], -1
	s_cbranch_vccnz .LBB0_621
	v_readlane_b32 s0, v254, 10
	v_readlane_b32 s1, v254, 11
	s_andn2_b64 vcc, exec, s[0:1]
	s_mov_b64 s[12:13], -1
	v_lshl_add_u32 v164, v168, 2, s14
	ds_read_b128 v[148:151], v164 offset:128
	ds_read_b128 v[152:155], v164 offset:160
	ds_read_b128 v[156:159], v164 offset:192
	ds_read_b128 v[164:167], v164 offset:224
	s_waitcnt lgkmcnt(3)
	v_add_f32_e32 v148, v252, v148
	v_add_f32_e32 v149, v252, v149
	v_add_f32_e32 v150, v252, v150
	v_add_f32_e32 v151, v252, v151
	s_waitcnt lgkmcnt(2)
	v_add_f32_e32 v152, v252, v152
	v_add_f32_e32 v153, v252, v153
	v_add_f32_e32 v154, v252, v154
	v_add_f32_e32 v155, v252, v155
	s_waitcnt lgkmcnt(1)
	v_add_f32_e32 v156, v252, v156
	v_add_f32_e32 v157, v252, v157
	v_add_f32_e32 v158, v252, v158
	v_add_f32_e32 v159, v252, v159
	s_waitcnt lgkmcnt(0)
	v_add_f32_e32 v164, v252, v164
	v_add_f32_e32 v165, v252, v165
	v_add_f32_e32 v166, v252, v166
	v_add_f32_e32 v167, v252, v167
	v_mul_f32_e32 v148, 0x3fb8aa3b, v148
	v_mul_f32_e32 v149, 0x3fb8aa3b, v149
	v_mul_f32_e32 v150, 0x3fb8aa3b, v150
	v_mul_f32_e32 v151, 0x3fb8aa3b, v151
	v_mul_f32_e32 v152, 0x3fb8aa3b, v152
	v_mul_f32_e32 v153, 0x3fb8aa3b, v153
	v_mul_f32_e32 v154, 0x3fb8aa3b, v154
	v_mul_f32_e32 v155, 0x3fb8aa3b, v155
	v_mul_f32_e32 v156, 0x3fb8aa3b, v156
	v_mul_f32_e32 v157, 0x3fb8aa3b, v157
	v_mul_f32_e32 v158, 0x3fb8aa3b, v158
	v_mul_f32_e32 v159, 0x3fb8aa3b, v159
	v_mul_f32_e32 v164, 0x3fb8aa3b, v164
	v_mul_f32_e32 v165, 0x3fb8aa3b, v165
	v_mul_f32_e32 v166, 0x3fb8aa3b, v166
	v_mul_f32_e32 v167, 0x3fb8aa3b, v167
	v_exp_f32_e32 v148, v148
	v_exp_f32_e32 v149, v149
	v_exp_f32_e32 v150, v150
	v_exp_f32_e32 v151, v151
	v_exp_f32_e32 v152, v152
	v_exp_f32_e32 v153, v153
	v_exp_f32_e32 v154, v154
	v_exp_f32_e32 v155, v155
	v_exp_f32_e32 v156, v156
	v_exp_f32_e32 v157, v157
	v_exp_f32_e32 v158, v158
	v_exp_f32_e32 v159, v159
	v_exp_f32_e32 v164, v164
	v_exp_f32_e32 v165, v165
	v_exp_f32_e32 v166, v166
	v_exp_f32_e32 v167, v167
	v_pk_mul_f32 v[148:149], v[16:17], v[148:149]
	v_pk_mul_f32 v[150:151], v[18:19], v[150:151]
	v_pk_mul_f32 v[152:153], v[20:21], v[152:153]
	v_pk_mul_f32 v[154:155], v[22:23], v[154:155]
	v_pk_mul_f32 v[156:157], v[24:25], v[156:157]
	v_pk_mul_f32 v[158:159], v[26:27], v[158:159]
	v_pk_mul_f32 v[164:165], v[28:29], v[164:165]
	v_pk_mul_f32 v[166:167], v[30:31], v[166:167]
.LBB0_586:
	s_and_b64 vcc, exec, s[0:1]
	s_cbranch_vccnz .LBB0_620
	v_sub_u32_e32 v232, v240, v168
	v_add_u32_e32 v232, 0xffffffe0, v232
	s_and_b64 vcc, exec, s[8:9]
	s_cbranch_vccz .Lp5_ge_1
	v_cmp_le_i32_e32 vcc, 0, v232
	v_cmp_le_i32_e64 s[0:1], 1, v232
	v_cmp_le_i32_e64 s[98:99], 2, v232
	v_cndmask_b32_e64 v148, 0, v148, vcc
	v_cndmask_b32_e64 v149, 0, v149, s[0:1]
	v_cndmask_b32_e64 v150, 0, v150, s[98:99]
	v_cmp_le_i32_e32 vcc, 3, v232
	v_cmp_le_i32_e64 s[0:1], 8, v232
	v_cmp_le_i32_e64 s[98:99], 9, v232
	v_cndmask_b32_e64 v151, 0, v151, vcc
	v_cndmask_b32_e64 v152, 0, v152, s[0:1]
	v_cndmask_b32_e64 v153, 0, v153, s[98:99]
	v_cmp_le_i32_e32 vcc, 10, v232
	v_cmp_le_i32_e64 s[0:1], 11, v232
	v_cmp_le_i32_e64 s[98:99], 16, v232
	v_cndmask_b32_e64 v154, 0, v154, vcc
	v_cndmask_b32_e64 v155, 0, v155, s[0:1]
	v_cndmask_b32_e64 v156, 0, v156, s[98:99]
	v_cmp_le_i32_e32 vcc, 17, v232
	v_cmp_le_i32_e64 s[0:1], 18, v232
	v_cmp_le_i32_e64 s[98:99], 19, v232
	v_cndmask_b32_e64 v157, 0, v157, vcc
	v_cndmask_b32_e64 v158, 0, v158, s[0:1]
	v_cndmask_b32_e64 v159, 0, v159, s[98:99]
	v_cmp_le_i32_e32 vcc, 24, v232
	v_cmp_le_i32_e64 s[0:1], 25, v232
	v_cmp_le_i32_e64 s[98:99], 26, v232
	v_cndmask_b32_e64 v164, 0, v164, vcc
	v_cndmask_b32_e64 v165, 0, v165, s[0:1]
	v_cndmask_b32_e64 v166, 0, v166, s[98:99]
	v_cmp_le_i32_e32 vcc, 27, v232
	s_nop 1
	v_cndmask_b32_e64 v167, 0, v167, vcc
	s_branch .LBB0_620

.LBB0_621:
	v_cndmask_b32_e64 v148, 0, 1, s[76:77]
	v_cndmask_b32_e64 v149, 0, 1, s[80:81]
	v_cndmask_b32_e64 v148, v148, v149, s[8:9]
	v_and_b32_e32 v148, 1, v148
	v_cmp_eq_u32_e32 vcc, 1, v148
	s_cbranch_vccnz .LBB0_660
	v_readlane_b32 s0, v254, 12
	v_readlane_b32 s1, v254, 13
	s_andn2_b64 vcc, exec, s[0:1]
	s_mov_b64 s[12:13], -1
	v_lshl_add_u32 v164, v168, 2, s14
	ds_read_b128 v[148:151], v164 offset:256
	ds_read_b128 v[152:155], v164 offset:288
	ds_read_b128 v[156:159], v164 offset:320
	ds_read_b128 v[164:167], v164 offset:352
	s_waitcnt lgkmcnt(3)
	v_add_f32_e32 v148, v252, v148
	v_add_f32_e32 v149, v252, v149
	v_add_f32_e32 v150, v252, v150
	v_add_f32_e32 v151, v252, v151
	s_waitcnt lgkmcnt(2)
	v_add_f32_e32 v152, v252, v152
	v_add_f32_e32 v153, v252, v153
	v_add_f32_e32 v154, v252, v154
	v_add_f32_e32 v155, v252, v155
	s_waitcnt lgkmcnt(1)
	v_add_f32_e32 v156, v252, v156
	v_add_f32_e32 v157, v252, v157
	v_add_f32_e32 v158, v252, v158
	v_add_f32_e32 v159, v252, v159
	s_waitcnt lgkmcnt(0)
	v_add_f32_e32 v164, v252, v164
	v_add_f32_e32 v165, v252, v165
	v_add_f32_e32 v166, v252, v166
	v_add_f32_e32 v167, v252, v167
	v_mul_f32_e32 v148, 0x3fb8aa3b, v148
	v_mul_f32_e32 v149, 0x3fb8aa3b, v149
	v_mul_f32_e32 v150, 0x3fb8aa3b, v150
	v_mul_f32_e32 v151, 0x3fb8aa3b, v151
	v_mul_f32_e32 v152, 0x3fb8aa3b, v152
	v_mul_f32_e32 v153, 0x3fb8aa3b, v153
	v_mul_f32_e32 v154, 0x3fb8aa3b, v154
	v_mul_f32_e32 v155, 0x3fb8aa3b, v155
	v_mul_f32_e32 v156, 0x3fb8aa3b, v156
	v_mul_f32_e32 v157, 0x3fb8aa3b, v157
	v_mul_f32_e32 v158, 0x3fb8aa3b, v158
	v_mul_f32_e32 v159, 0x3fb8aa3b, v159
	v_mul_f32_e32 v164, 0x3fb8aa3b, v164
	v_mul_f32_e32 v165, 0x3fb8aa3b, v165
	v_mul_f32_e32 v166, 0x3fb8aa3b, v166
	v_mul_f32_e32 v167, 0x3fb8aa3b, v167
	v_exp_f32_e32 v148, v148
	v_exp_f32_e32 v149, v149
	v_exp_f32_e32 v150, v150
	v_exp_f32_e32 v151, v151
	v_exp_f32_e32 v152, v152
	v_exp_f32_e32 v153, v153
	v_exp_f32_e32 v154, v154
	v_exp_f32_e32 v155, v155
	v_exp_f32_e32 v156, v156
	v_exp_f32_e32 v157, v157
	v_exp_f32_e32 v158, v158
	v_exp_f32_e32 v159, v159
	v_exp_f32_e32 v164, v164
	v_exp_f32_e32 v165, v165
	v_exp_f32_e32 v166, v166
	v_exp_f32_e32 v167, v167
	v_pk_mul_f32 v[148:149], v[32:33], v[148:149]
	v_pk_mul_f32 v[150:151], v[34:35], v[150:151]
	v_pk_mul_f32 v[152:153], v[36:37], v[152:153]
	v_pk_mul_f32 v[154:155], v[38:39], v[154:155]
	v_pk_mul_f32 v[156:157], v[40:41], v[156:157]
	v_pk_mul_f32 v[158:159], v[42:43], v[158:159]
	v_pk_mul_f32 v[164:165], v[44:45], v[164:165]
	v_pk_mul_f32 v[166:167], v[46:47], v[166:167]
.LBB0_624:
	s_and_b64 vcc, exec, s[0:1]
	s_cbranch_vccnz .LBB0_658
	v_sub_u32_e32 v232, v240, v168
	v_add_u32_e32 v232, 0xffffffc0, v232
	s_and_b64 vcc, exec, s[8:9]
	s_cbranch_vccz .Lp5_ge_2
	v_cmp_le_i32_e32 vcc, 0, v232
	v_cmp_le_i32_e64 s[0:1], 1, v232
	v_cmp_le_i32_e64 s[98:99], 2, v232
	v_cndmask_b32_e64 v148, 0, v148, vcc
	v_cndmask_b32_e64 v149, 0, v149, s[0:1]
	v_cndmask_b32_e64 v150, 0, v150, s[98:99]
	v_cmp_le_i32_e32 vcc, 3, v232
	v_cmp_le_i32_e64 s[0:1], 8, v232
	v_cmp_le_i32_e64 s[98:99], 9, v232
	v_cndmask_b32_e64 v151, 0, v151, vcc
	v_cndmask_b32_e64 v152, 0, v152, s[0:1]
	v_cndmask_b32_e64 v153, 0, v153, s[98:99]
	v_cmp_le_i32_e32 vcc, 10, v232
	v_cmp_le_i32_e64 s[0:1], 11, v232
	v_cmp_le_i32_e64 s[98:99], 16, v232
	v_cndmask_b32_e64 v154, 0, v154, vcc
	v_cndmask_b32_e64 v155, 0, v155, s[0:1]
	v_cndmask_b32_e64 v156, 0, v156, s[98:99]
	v_cmp_le_i32_e32 vcc, 17, v232
	v_cmp_le_i32_e64 s[0:1], 18, v232
	v_cmp_le_i32_e64 s[98:99], 19, v232
	v_cndmask_b32_e64 v157, 0, v157, vcc
	v_cndmask_b32_e64 v158, 0, v158, s[0:1]
	v_cndmask_b32_e64 v159, 0, v159, s[98:99]
	v_cmp_le_i32_e32 vcc, 24, v232
	v_cmp_le_i32_e64 s[0:1], 25, v232
	v_cmp_le_i32_e64 s[98:99], 26, v232
	v_cndmask_b32_e64 v164, 0, v164, vcc
	v_cndmask_b32_e64 v165, 0, v165, s[0:1]
	v_cndmask_b32_e64 v166, 0, v166, s[98:99]
	v_cmp_le_i32_e32 vcc, 27, v232
	s_nop 1
	v_cndmask_b32_e64 v167, 0, v167, vcc
	s_branch .LBB0_658

.LBB0_661:
	s_mov_b64 s[12:13], -1
	s_andn2_b64 vcc, exec, s[62:63]
	v_lshl_add_u32 v239, v168, 2, s14
	ds_read_b128 v[148:151], v239 offset:384
	ds_read_b128 v[152:155], v239 offset:416
	ds_read_b128 v[156:159], v239 offset:448
	ds_read_b128 v[164:167], v239 offset:480
	s_waitcnt lgkmcnt(3)
	v_add_f32_e32 v148, v252, v148
	v_add_f32_e32 v149, v252, v149
	v_add_f32_e32 v150, v252, v150
	v_add_f32_e32 v151, v252, v151
	s_waitcnt lgkmcnt(2)
	v_add_f32_e32 v152, v252, v152
	v_add_f32_e32 v153, v252, v153
	v_add_f32_e32 v154, v252, v154
	v_add_f32_e32 v155, v252, v155
	s_waitcnt lgkmcnt(1)
	v_add_f32_e32 v156, v252, v156
	v_add_f32_e32 v157, v252, v157
	v_add_f32_e32 v158, v252, v158
	v_add_f32_e32 v159, v252, v159
	s_waitcnt lgkmcnt(0)
	v_add_f32_e32 v164, v252, v164
	v_add_f32_e32 v165, v252, v165
	v_add_f32_e32 v166, v252, v166
	v_add_f32_e32 v167, v252, v167
	v_mul_f32_e32 v148, 0x3fb8aa3b, v148
	v_mul_f32_e32 v149, 0x3fb8aa3b, v149
	v_mul_f32_e32 v150, 0x3fb8aa3b, v150
	v_mul_f32_e32 v151, 0x3fb8aa3b, v151
	v_mul_f32_e32 v152, 0x3fb8aa3b, v152
	v_mul_f32_e32 v153, 0x3fb8aa3b, v153
	v_mul_f32_e32 v154, 0x3fb8aa3b, v154
	v_mul_f32_e32 v155, 0x3fb8aa3b, v155
	v_mul_f32_e32 v156, 0x3fb8aa3b, v156
	v_mul_f32_e32 v157, 0x3fb8aa3b, v157
	v_mul_f32_e32 v158, 0x3fb8aa3b, v158
	v_mul_f32_e32 v159, 0x3fb8aa3b, v159
	v_mul_f32_e32 v164, 0x3fb8aa3b, v164
	v_mul_f32_e32 v165, 0x3fb8aa3b, v165
	v_mul_f32_e32 v166, 0x3fb8aa3b, v166
	v_mul_f32_e32 v167, 0x3fb8aa3b, v167
	v_exp_f32_e32 v148, v148
	v_exp_f32_e32 v149, v149
	v_exp_f32_e32 v150, v150
	v_exp_f32_e32 v151, v151
	v_exp_f32_e32 v152, v152
	v_exp_f32_e32 v153, v153
	v_exp_f32_e32 v154, v154
	v_exp_f32_e32 v155, v155
	v_exp_f32_e32 v156, v156
	v_exp_f32_e32 v157, v157
	v_exp_f32_e32 v158, v158
	v_exp_f32_e32 v159, v159
	v_exp_f32_e32 v164, v164
	v_exp_f32_e32 v165, v165
	v_exp_f32_e32 v166, v166
	v_exp_f32_e32 v167, v167
	v_pk_mul_f32 v[148:149], v[48:49], v[148:149]
	v_pk_mul_f32 v[150:151], v[50:51], v[150:151]
	v_pk_mul_f32 v[152:153], v[52:53], v[152:153]
	v_pk_mul_f32 v[154:155], v[54:55], v[154:155]
	v_pk_mul_f32 v[156:157], v[56:57], v[156:157]
	v_pk_mul_f32 v[158:159], v[58:59], v[158:159]
	v_pk_mul_f32 v[164:165], v[60:61], v[164:165]
	v_pk_mul_f32 v[166:167], v[62:63], v[166:167]
.LBB0_663:
	s_and_b64 vcc, exec, s[62:63]
	s_cbranch_vccnz .LBB0_697
	v_sub_u32_e32 v232, v240, v168
	v_add_u32_e32 v232, 0xffffffa0, v232
	s_and_b64 vcc, exec, s[8:9]
	s_cbranch_vccz .Lp5_ge_3
	v_cmp_le_i32_e32 vcc, 0, v232
	v_cmp_le_i32_e64 s[0:1], 1, v232
	v_cmp_le_i32_e64 s[98:99], 2, v232
	v_cndmask_b32_e64 v148, 0, v148, vcc
	v_cndmask_b32_e64 v149, 0, v149, s[0:1]
	v_cndmask_b32_e64 v150, 0, v150, s[98:99]
	v_cmp_le_i32_e32 vcc, 3, v232
	v_cmp_le_i32_e64 s[0:1], 8, v232
	v_cmp_le_i32_e64 s[98:99], 9, v232
	v_cndmask_b32_e64 v151, 0, v151, vcc
	v_cndmask_b32_e64 v152, 0, v152, s[0:1]
	v_cndmask_b32_e64 v153, 0, v153, s[98:99]
	v_cmp_le_i32_e32 vcc, 10, v232
	v_cmp_le_i32_e64 s[0:1], 11, v232
	v_cmp_le_i32_e64 s[98:99], 16, v232
	v_cndmask_b32_e64 v154, 0, v154, vcc
	v_cndmask_b32_e64 v155, 0, v155, s[0:1]
	v_cndmask_b32_e64 v156, 0, v156, s[98:99]
	v_cmp_le_i32_e32 vcc, 17, v232
	v_cmp_le_i32_e64 s[0:1], 18, v232
	v_cmp_le_i32_e64 s[98:99], 19, v232
	v_cndmask_b32_e64 v157, 0, v157, vcc
	v_cndmask_b32_e64 v158, 0, v158, s[0:1]
	v_cndmask_b32_e64 v159, 0, v159, s[98:99]
	v_cmp_le_i32_e32 vcc, 24, v232
	v_cmp_le_i32_e64 s[0:1], 25, v232
	v_cmp_le_i32_e64 s[98:99], 26, v232
	v_cndmask_b32_e64 v164, 0, v164, vcc
	v_cndmask_b32_e64 v165, 0, v165, s[0:1]
	v_cndmask_b32_e64 v166, 0, v166, s[98:99]
	v_cmp_le_i32_e32 vcc, 27, v232
	s_nop 1
	v_cndmask_b32_e64 v167, 0, v167, vcc
	s_branch .LBB0_697

.LBB0_1290:
	v_ashrrev_i32_e32 v0, 31, v140
	v_lshrrev_b32_e32 v0, 26, v0
	v_add_u32_e32 v0, v140, v0
	v_ashrrev_i32_e32 v1, 6, v0
	v_bfe_i32 v0, v140, 27, 1
	v_lshlrev_b32_e32 v20, 4, v140
	v_lshrrev_b32_e32 v0, 22, v0
	v_add_u32_e32 v0, v20, v0
	v_and_b32_e32 v0, 0xfffffc00, v0
	v_sub_u32_e32 v0, v20, v0
	v_lshrrev_b32_e32 v2, 4, v0
	v_bitop3_b32 v2, v2, v0, 32 bitop3:0x6c
	v_ashrrev_i32_e32 v0, 31, v0
	v_lshrrev_b32_e32 v0, 26, v0
	v_lshlrev_b32_e32 v3, 3, v1
	v_add_u32_e32 v0, v2, v0
	v_and_b32_e32 v3, -16, v3
	s_waitcnt vmcnt(0)
	v_ashrrev_i32_e32 v4, 6, v0
	v_add_u32_e32 v0, v4, v3
	v_mul_i32_i24_e32 v3, 64, v4
	v_lshlrev_b32_e32 v1, 5, v1
	v_sub_u32_e32 v2, v2, v3
	v_mov_b32_e32 v7, 1
	v_and_b32_e32 v1, 32, v1
	v_ashrrev_i16_sdwa v2, v7, sext(v2) dst_sel:DWORD dst_unused:UNUSED_PAD src0_sel:DWORD src1_sel:BYTE_0
	v_add_u32_sdwa v2, v1, sext(v2) dst_sel:DWORD dst_unused:UNUSED_PAD src0_sel:DWORD src1_sel:WORD_0
	v_add_u32_e32 v1, 0x2000, v20
	v_ashrrev_i32_e32 v3, 31, v1
	v_lshrrev_b32_e32 v3, 22, v3
	v_add_u32_e32 v3, v1, v3
	v_ashrrev_i32_e32 v3, 10, v3
	v_mul_i32_i24_e32 v4, 0x400, v3
	v_sub_u32_e32 v1, v1, v4
	v_lshrrev_b32_e32 v4, 4, v1
	s_add_i32 s1, s0, s1
	v_bitop3_b32 v1, v4, v1, 32 bitop3:0x6c
	s_mul_hi_i32 s0, s1, 0x78787879
	v_ashrrev_i32_e32 v5, 31, v1
	s_lshr_b32 s2, s0, 31
	s_ashr_i32 s0, s0, 5
	v_lshrrev_b32_e32 v5, 26, v5
	s_add_i32 s2, s0, s2
	v_add_u32_e32 v5, v1, v5
	s_lshl_b32 s6, s2, 2
	v_ashrrev_i32_e32 v6, 6, v5
	v_and_b32_e32 v5, 0xc0, v5
	s_sub_i32 s0, 0x42, s6
	v_sub_u32_e32 v1, v1, v5
	s_min_u32 s7, s0, 4
	s_mul_i32 s3, s2, 0x44
	v_ashrrev_i16_sdwa v1, v7, sext(v1) dst_sel:DWORD dst_unused:UNUSED_PAD src0_sel:DWORD src1_sel:BYTE_0
	s_sub_i32 s14, s1, s3
	v_cvt_f32_ubyte0_e32 v7, s7
	v_cvt_f32_i32_e32 v5, s14
	v_rcp_iflag_f32_e32 v8, v7
	v_lshlrev_b32_e32 v4, 3, v3
	v_lshlrev_b32_e32 v3, 5, v3
	v_and_b32_e32 v4, -16, v4
	v_and_b32_e32 v3, 32, v3
	v_add_u32_e32 v4, v6, v4
	v_add_u32_sdwa v6, v3, sext(v1) dst_sel:DWORD dst_unused:UNUSED_PAD src0_sel:DWORD src1_sel:WORD_0
	v_mul_f32_e32 v1, v5, v8
	v_trunc_f32_e32 v1, v1
	v_fma_f32 v3, -v1, v7, v5
	v_cvt_i32_f32_e32 v1, v1
	s_ashr_i32 s0, s14, 30
	s_or_b32 s0, s0, 1
	v_cmp_ge_f32_e64 s[4:5], |v3|, v7
	s_and_b64 s[4:5], s[4:5], exec
	s_cselect_b32 s0, s0, 0
	v_readfirstlane_b32 s4, v1
	s_add_i32 s0, s4, s0
	s_mul_i32 s22, s0, s7
	s_sext_i32_i8 s4, s0
	s_sub_i32 s5, s14, s22
	s_sext_i32_i8 s5, s5
	s_lshl_b32 s4, s4, 8
	s_add_i32 s6, s6, s5
	s_ashr_i32 s5, s4, 31
	s_lshl_b32 s6, s6, 8
	s_lshl_b64 s[14:15], s[4:5], 11
	s_add_u32 s18, s46, s14
	v_ashrrev_i32_e32 v1, 31, v0
	v_ashrrev_i32_e32 v5, 31, v4
	s_addc_u32 s19, s47, s15
	v_lshlrev_b64 v[0:1], 11, v[0:1]
	v_lshlrev_b64 v[4:5], 11, v[4:5]
	s_ashr_i32 s7, s6, 31
	v_lshl_add_u64 v[8:9], s[18:19], 0, v[0:1]
	v_lshl_add_u64 v[10:11], s[18:19], 0, v[4:5]
	s_lshl_b64 s[18:19], s[6:7], 11
	s_add_u32 s18, s44, s18
	s_addc_u32 s19, s45, s19
	v_readlane_b32 s5, v254, 61
	v_lshl_add_u64 v[12:13], s[18:19], 0, v[0:1]
	v_lshl_add_u64 v[14:15], s[18:19], 0, v[4:5]
	s_or_b32 s18, s4, 0x80
	v_add_u32_e32 v144, s5, v20
	v_ashrrev_i32_e32 v3, 31, v2
	s_ashr_i32 s19, s18, 31
	v_lshlrev_b64 v[2:3], 1, v[2:3]
	v_readfirstlane_b32 s5, v144
	v_ashrrev_i32_e32 v7, 31, v6
	v_add_u32_e32 v149, 0x2000, v144
	s_lshl_b64 s[18:19], s[18:19], 11
	v_lshl_add_u64 v[8:9], v[8:9], 0, v[2:3]
	s_mov_b32 m0, s5
	v_lshlrev_b64 v[6:7], 1, v[6:7]
	v_readfirstlane_b32 s5, v149
	v_add_u32_e32 v150, 0, v20
	s_add_u32 s18, s46, s18
	global_load_lds_dwordx4 v[8:9], off
	v_lshl_add_u64 v[10:11], v[10:11], 0, v[6:7]
	s_mov_b32 m0, s5
	v_readfirstlane_b32 s5, v150
	v_add_u32_e32 v151, 0x2000, v150
	s_addc_u32 s19, s47, s19
	global_load_lds_dwordx4 v[10:11], off
	v_lshl_add_u64 v[12:13], v[12:13], 0, v[2:3]
	s_mov_b32 m0, s5
	v_readfirstlane_b32 s5, v151
	v_lshl_add_u64 v[16:17], s[18:19], 0, v[0:1]
	v_lshl_add_u64 v[18:19], s[18:19], 0, v[4:5]
	s_or_b32 s18, s6, 0x80
	global_load_lds_dwordx4 v[12:13], off
	s_mov_b32 m0, s5
	v_readlane_b32 s5, v254, 62
	s_ashr_i32 s19, s18, 31
	s_lshl_b64 s[18:19], s[18:19], 11
	v_add_u32_e32 v153, s5, v20
	v_lshl_add_u64 v[14:15], v[14:15], 0, v[6:7]
	v_readfirstlane_b32 s5, v153
	v_add_u32_e32 v154, 0x2000, v153
	s_add_u32 s18, s44, s18
	global_load_lds_dwordx4 v[14:15], off
	v_lshl_add_u64 v[16:17], v[16:17], 0, v[2:3]
	s_mov_b32 m0, s5
	v_readfirstlane_b32 s5, v154
	s_addc_u32 s19, s45, s19
	v_add_u32_e32 v156, 0x4000, v150
	global_load_lds_dwordx4 v[16:17], off
	v_lshl_add_u64 v[18:19], v[18:19], 0, v[6:7]
	s_mov_b32 m0, s5
	v_lshl_add_u64 v[22:23], s[18:19], 0, v[0:1]
	v_readfirstlane_b32 s5, v156
	v_add_u32_e32 v157, 0x6000, v150
	global_load_lds_dwordx4 v[18:19], off
	v_lshl_add_u64 v[128:129], v[22:23], 0, v[2:3]
	s_mov_b32 m0, s5
	v_lshl_add_u64 v[22:23], s[18:19], 0, v[4:5]
	v_readfirstlane_b32 s5, v157
	global_load_lds_dwordx4 v[128:129], off
	v_lshl_add_u64 v[130:131], v[22:23], 0, v[6:7]
	s_mov_b32 m0, s5
	v_ashrrev_i32_e32 v21, 8, v140
	global_load_lds_dwordx4 v[130:131], off
	v_mov_b32_e32 v23, 0
	v_mov_b32_e32 v24, 0
	v_mov_b32_e32 v25, 0
	v_mov_b32_e32 v26, 0
	v_mov_b32_e32 v27, 0
	v_mov_b32_e32 v28, 0
	v_mov_b32_e32 v29, 0
	v_mov_b32_e32 v30, 0
	v_mov_b32_e32 v31, 0
	v_mov_b32_e32 v32, 0
	v_mov_b32_e32 v33, 0
	v_mov_b32_e32 v34, 0
	v_mov_b32_e32 v35, 0
	v_mov_b32_e32 v36, 0
	v_mov_b32_e32 v37, 0
	v_mov_b32_e32 v38, 0
	v_mov_b32_e32 v39, 0
	v_mov_b32_e32 v40, 0
	v_mov_b32_e32 v41, 0
	v_mov_b32_e32 v42, 0
	v_mov_b32_e32 v43, 0
	v_mov_b32_e32 v44, 0
	v_mov_b32_e32 v45, 0
	v_mov_b32_e32 v46, 0
	v_mov_b32_e32 v47, 0
	v_mov_b32_e32 v48, 0
	v_mov_b32_e32 v49, 0
	v_mov_b32_e32 v50, 0
	v_mov_b32_e32 v51, 0
	v_mov_b32_e32 v52, 0
	v_mov_b32_e32 v53, 0
	v_mov_b32_e32 v54, 0
	v_mov_b32_e32 v55, 0
	v_mov_b32_e32 v56, 0
	v_mov_b32_e32 v57, 0
	v_mov_b32_e32 v58, 0
	v_mov_b32_e32 v59, 0
	v_mov_b32_e32 v60, 0
	v_mov_b32_e32 v61, 0
	v_mov_b32_e32 v62, 0
	v_mov_b32_e32 v63, 0
	v_mov_b32_e32 v64, 0
	v_mov_b32_e32 v65, 0
	v_mov_b32_e32 v66, 0
	v_mov_b32_e32 v67, 0
	v_mov_b32_e32 v68, 0
	v_mov_b32_e32 v69, 0
	v_mov_b32_e32 v70, 0
	v_mov_b32_e32 v71, 0
	v_mov_b32_e32 v72, 0
	v_mov_b32_e32 v73, 0
	v_mov_b32_e32 v74, 0
	v_mov_b32_e32 v75, 0
	v_mov_b32_e32 v76, 0
	v_mov_b32_e32 v77, 0
	v_mov_b32_e32 v78, 0
	v_mov_b32_e32 v79, 0
	v_mov_b32_e32 v80, 0
	v_mov_b32_e32 v81, 0
	v_mov_b32_e32 v82, 0
	v_mov_b32_e32 v83, 0
	v_mov_b32_e32 v84, 0
	v_mov_b32_e32 v85, 0
	v_mov_b32_e32 v86, 0
	v_mov_b32_e32 v87, 0
	v_mov_b32_e32 v88, 0
	v_mov_b32_e32 v89, 0
	v_mov_b32_e32 v90, 0
	v_mov_b32_e32 v91, 0
	v_mov_b32_e32 v92, 0
	v_mov_b32_e32 v93, 0
	v_mov_b32_e32 v94, 0
	v_mov_b32_e32 v95, 0
	v_mov_b32_e32 v96, 0
	v_mov_b32_e32 v97, 0
	v_mov_b32_e32 v98, 0
	v_mov_b32_e32 v99, 0
	v_mov_b32_e32 v100, 0
	v_mov_b32_e32 v101, 0
	v_mov_b32_e32 v102, 0
	v_mov_b32_e32 v103, 0
	v_mov_b32_e32 v104, 0
	v_mov_b32_e32 v105, 0
	v_mov_b32_e32 v106, 0
	v_mov_b32_e32 v107, 0
	v_mov_b32_e32 v108, 0
	v_mov_b32_e32 v109, 0
	v_mov_b32_e32 v110, 0
	v_mov_b32_e32 v111, 0
	v_mov_b32_e32 v112, 0
	v_mov_b32_e32 v113, 0
	v_mov_b32_e32 v114, 0
	v_mov_b32_e32 v115, 0
	v_mov_b32_e32 v116, 0
	v_mov_b32_e32 v117, 0
	v_mov_b32_e32 v118, 0
	v_mov_b32_e32 v119, 0
	v_mov_b32_e32 v120, 0
	v_mov_b32_e32 v121, 0
	v_mov_b32_e32 v122, 0
	v_mov_b32_e32 v123, 0
	v_mov_b32_e32 v124, 0
	v_mov_b32_e32 v125, 0
	v_mov_b32_e32 v126, 0
	v_mov_b32_e32 v127, 0
	v_mov_b32_e32 v245, 0x7fc00000
	v_not_b32_e32 v246, 31
	v_not_b32_e32 v244, 63
	v_cmp_eq_u32_e32 vcc, 1, v21
	s_and_saveexec_b64 s[18:19], vcc
	s_cbranch_execz .LBB0_1292
	s_barrier
.LBB0_1292:
	s_or_b64 exec, exec, s[18:19]
	v_readlane_b32 s7, v254, 63
	s_mov_b64 s[24:25], 0x80
	v_lshl_add_u64 v[8:9], v[8:9], 0, s[24:25]
	v_add_u32_e32 v158, s7, v20
	v_add_u32_e32 v159, 0x2000, v158
	v_readfirstlane_b32 s5, v158
	s_mov_b32 m0, s5
	v_readfirstlane_b32 s5, v159
	v_add_u32_e32 v160, 0x8000, v150
	s_waitcnt vmcnt(4)
	s_barrier
	global_load_lds_dwordx4 v[8:9], off
	v_lshl_add_u64 v[8:9], v[10:11], 0, s[24:25]
	s_mov_b32 m0, s5
	v_readfirstlane_b32 s5, v160
	v_add_u32_e32 v164, 0xa000, v150
	v_readlane_b32 s18, v255, 0
	global_load_lds_dwordx4 v[8:9], off
	v_lshl_add_u64 v[8:9], v[12:13], 0, s[24:25]
	s_mov_b32 m0, s5
	v_readfirstlane_b32 s5, v164
	v_add_u32_e32 v165, s18, v20
	global_load_lds_dwordx4 v[8:9], off
	v_lshl_add_u64 v[8:9], v[14:15], 0, s[24:25]
	s_mov_b32 m0, s5
	v_readfirstlane_b32 s5, v165
	v_add_u32_e32 v166, 0x2000, v165
	global_load_lds_dwordx4 v[8:9], off
	v_lshl_add_u64 v[8:9], v[16:17], 0, s[24:25]
	s_mov_b32 m0, s5
	v_readfirstlane_b32 s5, v166
	global_load_lds_dwordx4 v[8:9], off
	v_lshl_add_u64 v[8:9], v[18:19], 0, s[24:25]
	s_mov_b32 m0, s5
	s_sub_i32 s1, s1, s22
	global_load_lds_dwordx4 v[8:9], off
	v_and_b32_e32 v22, 15, v140
	v_bfe_u32 v142, v140, 4, 2
	v_lshlrev_b32_e32 v11, 2, v140
	s_sub_i32 s1, s1, s3
	v_lshlrev_b32_e32 v8, 4, v142
	v_lshlrev_b32_e32 v9, 6, v22
	v_and_b32_e32 v11, 32, v11
	s_sext_i32_i8 s1, s1
	v_bitop3_b32 v9, v8, v11, v9 bitop3:0x36
	v_readlane_b32 s5, v254, 61
	s_lshl_b32 s2, s2, 10
	s_lshl_b32 s1, s1, 8
	v_add_u32_e32 v12, s5, v9
	v_readlane_b32 s5, v254, 62
	s_add_i32 s2, s2, s1
	v_add_u32_e32 v14, s7, v9
	v_add_u32_e32 v13, s5, v9
	v_add_u32_e32 v15, s18, v9
	v_add_u32_e32 v17, 0, v9
	v_lshlrev_b32_e32 v9, 6, v140
	s_movk_i32 s5, 0x3c0
	s_ashr_i32 s3, s2, 31
	v_and_or_b32 v8, v9, s5, v8
	s_lshl_b64 s[2:3], s[2:3], 11
	v_xad_u32 v11, v8, v11, 0
	v_lshl_add_u64 v[8:9], s[2:3], 0, v[4:5]
	v_lshl_add_u64 v[8:9], v[8:9], 0, v[6:7]
	v_lshl_add_u64 v[132:133], s[44:45], 0, v[8:9]
	v_lshl_add_u64 v[8:9], s[2:3], 0, v[0:1]
	v_lshl_add_u64 v[0:1], s[14:15], 0, v[0:1]
	v_bfe_u32 v141, v140, 6, 2
	s_waitcnt vmcnt(6)
	v_lshlrev_b32_e32 v16, 13, v21
	v_lshl_add_u64 v[4:5], s[14:15], 0, v[4:5]
	v_lshl_add_u64 v[0:1], v[0:1], 0, v[2:3]
	v_lshlrev_b32_e32 v10, 12, v141
	v_or_b32_e32 v18, 0x800, v16
	v_or_b32_e32 v19, 0x1000, v16
	v_or_b32_e32 v20, 0x1800, v16
	v_lshl_add_u64 v[8:9], v[8:9], 0, v[2:3]
	v_lshl_add_u64 v[4:5], v[4:5], 0, v[6:7]
	v_lshl_add_u64 v[138:139], s[46:47], 0, v[0:1]
	v_mov_b32_e32 v0, 0
	s_lshl_b32 s0, s0, 24
	v_lshl_or_b32 v143, v21, 6, v22
	v_lshl_add_u64 v[134:135], s[44:45], 0, v[8:9]
	v_lshl_add_u64 v[136:137], s[46:47], 0, v[4:5]
	s_mov_b32 s1, -2
	s_mov_b64 s[14:15], 0
	v_add_u32_e32 v168, v12, v10
	v_add_u32_e32 v148, v17, v16
	v_add_u32_e32 v147, v11, v18
	v_add_u32_e32 v146, v11, v19
	v_add_u32_e32 v145, v11, v20
	v_add_u32_e32 v167, v13, v10
	v_add_u32_e32 v155, v14, v10
	v_add_u32_e32 v152, v15, v10
	v_mov_b32_e32 v1, v0
	v_mov_b32_e32 v2, v0
	v_mov_b32_e32 v3, v0
	v_mov_b32_e32 v4, v0
	v_mov_b32_e32 v5, v0
	v_mov_b32_e32 v6, v0
	v_mov_b32_e32 v7, v0
	v_mov_b32_e32 v8, v0
	v_mov_b32_e32 v9, v0
	v_mov_b32_e32 v10, v0
	v_mov_b32_e32 v11, v0
	v_mov_b32_e32 v12, v0
	v_mov_b32_e32 v13, v0
	v_mov_b32_e32 v14, v0
	v_mov_b32_e32 v15, v0
	v_mov_b32_e32 v16, v0
	v_mov_b32_e32 v17, v0
	v_mov_b32_e32 v18, v0
	v_mov_b32_e32 v19, v0
	v_mov_b32_e32 v20, v0
	v_mov_b32_e32 v21, v0
	v_mov_b32_e32 v22, v0
	s_mov_b64 s[18:19], 0x40180
	s_barrier
